# attention loop: extra mid-QK barrier (keeps SIMD wave pairs interleaved) + static setprio 1 for waves 4-7; conflict-free K swizzle; DMAs spread into gaps
# speedup vs baseline: 1.0070x; 1.0070x over previous
; __device__ __forceinline__ float bflo(unsigned w) { return __uint_as_float(w << 16); }
; __device__ __forceinline__ float bfhi(unsigned w) { return __uint_as_float(w & 0xffff0000u); }
; #define QROPE(RW, GA, GB, E2, OUT) do { int pp = (8 * d0 + 4 * hi + (E2)) & 31; asm volatile("" : "+v"(pp)); const float freq = __builtin_amdgcn_exp2f(-(float)pp * (13.287712379549449f / 32.f)); \
;         float sn, cs; sincos_rev(idx * freq * INV2PI, sn, cs); const float y0 = bflo(RW) * rsc * (GA), y1 = bfhi(RW) * rsc * (GB); OUT = cvtpk(y0 * cs - y1 * sn, y0 * sn + y1 * cs); } while (0)
; __device__ __forceinline__ void attn_unit_fast(const bf16* __restrict__ Qb, const bf16* __restrict__ Kh, const bf16* __restrict__ Vh, bf16* __restrict__ Ob, int NT, char* lds, int t0, const float* __restrict__ qg) {
;     ...
;   const bf16* Qw = Qb + (long)(wid * QBLK + r32) * LDQ + hi * 8;
;   {
;     float ssq = 0.f;
; #pragma unroll
;     for (int d0 = 0; d0 < 8; ++d0) { const v4u rw = *reinterpret_cast<const v4u*>(Qw + d0 * 16);
;       ssq += (bflo(rw.x) * bflo(rw.x) + bfhi(rw.x) * bfhi(rw.x)) + (bflo(rw.y) * bflo(rw.y) + bfhi(rw.y) * bfhi(rw.y));
;       ssq += (bflo(rw.z) * bflo(rw.z) + bfhi(rw.z) * bfhi(rw.z)) + (bflo(rw.w) * bflo(rw.w) + bfhi(rw.w) * bfhi(rw.w)); }
;     { auto rr = __builtin_amdgcn_permlane32_swap(__float_as_uint(ssq), __float_as_uint(ssq), false, false); ssq = __uint_as_float(rr[0]) + __uint_as_float(rr[1]); }
;     const float rsc = (SCALE * 1.4426950408889634f) / sqrtf(ssq * (1.f / 128.f) + EPS);
;     const int t = t0 + wid * QBLK + r32; const float frow = (float)(t >> 6), fcol = (float)(t & 63);
; #pragma unroll
;     for (int d0 = 0; d0 < 8; ++d0) { const v4u rw = *reinterpret_cast<const v4u*>(Qw + d0 * 16);
;       const f32x4 g0 = *reinterpret_cast<const f32x4*>(qg + 16 * d0 + 8 * hi), g1 = *reinterpret_cast<const f32x4*>(qg + 16 * d0 + 8 * hi + 4);
;       const float idx = d0 < 4 ? frow : fcol; v4u wv;
;     ...
;       QROPE(rw.x, g0.x, g0.y, 0, wv.x); QROPE(rw.y, g0.z, g0.w, 1, wv.y); QROPE(rw.z, g1.x, g1.y, 2, wv.z); QROPE(rw.w, g1.z, g1.w, 3, wv.w);
.LBB0_451:
	v_mov_b32_e32 v195, v252
	s_lshl_b64 s[0:1], s[20:21], 1
	v_ashrrev_i32_e32 v0, 1, v195
	v_bfe_u32 v193, v195, 5, 1
	v_and_b32_e32 v178, 0xffffffe0, v0
	v_bfi_b32 v2, s3, v0, v195
	v_mov_b64_e32 v[0:1], s[68:69]
	v_mad_i64_i32 v[0:1], s[4:5], v2, s53, v[0:1]
	v_lshlrev_b32_e32 v176, 4, v193
	v_lshlrev_b32_e32 v16, 2, v193
	v_and_b32_e32 v191, 31, v195
	v_lshl_add_u64 v[0:1], v[0:1], 0, v[176:177]
	v_and_b32_e32 v95, 32, v195
	v_mov_b32_e32 v2, v16
	global_load_dwordx4 v[56:59], v[0:1], off
	global_load_dwordx4 v[60:63], v[0:1], off offset:32
	global_load_dwordx4 v[64:67], v[0:1], off offset:64
	global_load_dwordx4 v[68:71], v[0:1], off offset:96
	global_load_dwordx4 v[72:75], v[0:1], off offset:128
	global_load_dwordx4 v[76:79], v[0:1], off offset:160
	global_load_dwordx4 v[80:83], v[0:1], off offset:192
	global_load_dwordx4 v[84:87], v[0:1], off offset:224
	v_or_b32_e32 v0, s85, v191
	global_load_dwordx4 v[32:35], v95, s[22:23] offset:16
	global_load_dwordx4 v[48:51], v95, s[22:23]
	v_add_u32_e32 v0, v0, v178
	v_cvt_f32_i32_e32 v2, v2
	v_ashrrev_i32_e32 v1, 6, v0
	v_or_b32_e32 v17, 1, v16
	v_cvt_f32_i32_e32 v8, v1
	v_mov_b32_e32 v1, v17
	v_and_b32_e32 v0, 63, v0
	v_cvt_f32_ubyte0_e32 v93, v0
	v_mul_f32_e32 v0, 0xbed49a78, v2
	v_cvt_f32_i32_e32 v1, v1
	v_exp_f32_e32 v0, v0
	v_or_b32_e32 v18, 2, v16
	v_or_b32_e32 v19, 3, v16
	v_mul_f32_e32 v1, 0xbed49a78, v1
	v_mul_f32_e32 v0, v0, v8
	v_exp_f32_e32 v1, v1
	v_mul_f32_e32 v2, 0.15915494, v0
	v_floor_f32_e32 v2, v2
	v_fma_f32 v0, v0, 0.15915494, -v2
	v_mov_b32_e32 v2, v18
	v_sin_f32_e32 v164, v0
	v_cos_f32_e32 v160, v0
	v_mul_f32_e32 v0, v1, v8
	v_mul_f32_e32 v1, 0.15915494, v0
	v_cvt_f32_i32_e32 v2, v2
	v_floor_f32_e32 v1, v1
	v_fma_f32 v0, v0, 0.15915494, -v1
	v_mov_b32_e32 v1, v19
	v_sin_f32_e32 v156, v0
	v_cos_f32_e32 v112, v0
	v_mul_f32_e32 v0, 0xbed49a78, v2
	v_cvt_f32_i32_e32 v1, v1
	v_exp_f32_e32 v0, v0
	v_or_b32_e32 v24, 8, v16
	global_load_dwordx4 v[36:39], v95, s[22:23] offset:80
	global_load_dwordx4 v[40:43], v95, s[22:23] offset:64
	v_mul_f32_e32 v1, 0xbed49a78, v1
	v_mul_f32_e32 v0, v0, v8
	v_exp_f32_e32 v1, v1
	v_mul_f32_e32 v2, 0.15915494, v0
	v_floor_f32_e32 v2, v2
	v_fma_f32 v0, v0, 0.15915494, -v2
	v_mov_b32_e32 v2, v24
	v_sin_f32_e32 v126, v0
	v_cos_f32_e32 v114, v0
	v_mul_f32_e32 v0, v1, v8
	v_mul_f32_e32 v1, 0.15915494, v0
	v_cvt_f32_i32_e32 v2, v2
	v_floor_f32_e32 v1, v1
	v_or_b32_e32 v25, 9, v16
	v_fma_f32 v0, v0, 0.15915494, -v1
	v_mov_b32_e32 v1, v25
	v_sin_f32_e32 v118, v0
	v_cos_f32_e32 v116, v0
	v_mul_f32_e32 v0, 0xbed49a78, v2
	v_cvt_f32_i32_e32 v1, v1
	v_exp_f32_e32 v0, v0
	v_or_b32_e32 v26, 10, v16
	v_or_b32_e32 v27, 11, v16
	v_mul_f32_e32 v1, 0xbed49a78, v1
	v_mul_f32_e32 v0, v0, v8
	v_exp_f32_e32 v1, v1
	v_mul_f32_e32 v2, 0.15915494, v0
	v_floor_f32_e32 v2, v2
	v_fma_f32 v0, v0, 0.15915494, -v2
	v_mov_b32_e32 v2, v26
	v_sin_f32_e32 v122, v0
	v_cos_f32_e32 v120, v0
	v_mul_f32_e32 v0, v1, v8
	v_mul_f32_e32 v1, 0.15915494, v0
	v_cvt_f32_i32_e32 v2, v2
	v_floor_f32_e32 v1, v1
	v_fma_f32 v0, v0, 0.15915494, -v1
	v_mov_b32_e32 v1, v27
	v_sin_f32_e32 v128, v0
	v_cos_f32_e32 v124, v0
	v_mul_f32_e32 v0, 0xbed49a78, v2
	v_cvt_f32_i32_e32 v1, v1
	v_exp_f32_e32 v0, v0
	v_or_b32_e32 v88, 16, v16
	global_load_dwordx4 v[44:47], v95, s[22:23] offset:144
	global_load_dwordx4 v[52:55], v95, s[22:23] offset:128
	v_mul_f32_e32 v1, 0xbed49a78, v1
	v_mul_f32_e32 v0, v0, v8
	v_exp_f32_e32 v1, v1
	v_mul_f32_e32 v2, 0.15915494, v0
	v_floor_f32_e32 v2, v2
	v_fma_f32 v0, v0, 0.15915494, -v2
	v_mov_b32_e32 v2, v88
	v_sin_f32_e32 v162, v0
	v_cos_f32_e32 v158, v0
	v_mul_f32_e32 v0, v1, v8
	v_mul_f32_e32 v1, 0.15915494, v0
	v_cvt_f32_i32_e32 v2, v2
	v_floor_f32_e32 v1, v1
	v_or_b32_e32 v111, 17, v16
	v_fma_f32 v0, v0, 0.15915494, -v1
	v_mov_b32_e32 v1, v111
	v_sin_f32_e32 v168, v0
	v_cos_f32_e32 v166, v0
	v_mul_f32_e32 v0, 0xbed49a78, v2
	v_cvt_f32_i32_e32 v1, v1
	v_exp_f32_e32 v0, v0
	v_or_b32_e32 v109, 18, v16
	v_or_b32_e32 v107, 19, v16
	v_mul_f32_e32 v1, 0xbed49a78, v1
	v_mul_f32_e32 v0, v0, v8
	v_exp_f32_e32 v1, v1
	v_mul_f32_e32 v2, 0.15915494, v0
	v_floor_f32_e32 v2, v2
	v_fma_f32 v0, v0, 0.15915494, -v2
	v_sin_f32_e32 v172, v0
	v_cos_f32_e32 v170, v0
	v_mul_f32_e32 v0, v1, v8
	v_mov_b32_e32 v2, v109
	v_mul_f32_e32 v1, 0.15915494, v0
	v_floor_f32_e32 v1, v1
	v_cvt_f32_i32_e32 v2, v2
	v_fma_f32 v0, v0, 0.15915494, -v1
	v_mov_b32_e32 v1, v107
	v_sin_f32_e32 v180, v0
	v_cvt_f32_i32_e32 v1, v1
	v_cos_f32_e32 v174, v0
	v_mul_f32_e32 v0, 0xbed49a78, v2
	v_exp_f32_e32 v0, v0
	v_mul_f32_e32 v1, 0xbed49a78, v1
	v_exp_f32_e32 v1, v1
	v_or_b32_e32 v99, 24, v16
	v_mul_f32_e32 v0, v0, v8
	v_mul_f32_e32 v2, 0.15915494, v0
	v_floor_f32_e32 v2, v2
	v_fma_f32 v0, v0, 0.15915494, -v2
	v_mul_f32_e32 v9, v1, v8
	v_sin_f32_e32 v186, v0
	v_cos_f32_e32 v184, v0
	v_mul_f32_e32 v0, 0.15915494, v9
	v_mov_b32_e32 v11, v99
	v_floor_f32_e32 v10, v0
	global_load_dwordx4 v[0:3], v95, s[22:23] offset:208
	global_load_dwordx4 v[4:7], v95, s[22:23] offset:192
	v_or_b32_e32 v97, 25, v16
	v_cvt_f32_i32_e32 v11, v11
	v_fma_f32 v9, v9, 0.15915494, -v10
	v_mov_b32_e32 v10, v97
	v_sin_f32_e32 v190, v9
	v_cos_f32_e32 v188, v9
	v_mul_f32_e32 v9, 0xbed49a78, v11
	v_cvt_f32_i32_e32 v10, v10
	v_exp_f32_e32 v9, v9
	v_or_b32_e32 v103, 26, v16
	v_or_b32_e32 v105, 27, v16
	v_mul_f32_e32 v10, 0xbed49a78, v10
	v_mul_f32_e32 v9, v9, v8
	v_exp_f32_e32 v10, v10
	v_mul_f32_e32 v11, 0.15915494, v9
	v_floor_f32_e32 v11, v11
	v_fma_f32 v9, v9, 0.15915494, -v11
	v_mov_b32_e32 v11, v103
	v_sin_f32_e32 v194, v9
	v_cos_f32_e32 v192, v9
	v_mul_f32_e32 v9, v10, v8
	v_mul_f32_e32 v10, 0.15915494, v9
	v_cvt_f32_i32_e32 v11, v11
	v_floor_f32_e32 v10, v10
	v_fma_f32 v9, v9, 0.15915494, -v10
	v_mov_b32_e32 v10, v105
	v_sin_f32_e32 v94, v9
	v_cos_f32_e32 v92, v9
	v_mul_f32_e32 v9, 0xbed49a78, v11
	v_cvt_f32_i32_e32 v10, v10
	v_exp_f32_e32 v9, v9
	s_waitcnt vmcnt(0)
; __device__ __forceinline__ float bflo(unsigned w) { return __uint_as_float(w << 16); }
; __device__ __forceinline__ float bfhi(unsigned w) { return __uint_as_float(w & 0xffff0000u); }
; __device__ __forceinline__ void attn_unit_fast(const bf16* __restrict__ Qb, const bf16* __restrict__ Kh, const bf16* __restrict__ Vh, bf16* __restrict__ Ob, int NT, char* lds, int t0, const float* __restrict__ qg) {
;     ...
;     for (int d0 = 0; d0 < 8; ++d0) { const v4u rw = *reinterpret_cast<const v4u*>(Qw + d0 * 16);
;       ssq += (bflo(rw.x) * bflo(rw.x) + bfhi(rw.x) * bfhi(rw.x)) + (bflo(rw.y) * bflo(rw.y) + bfhi(rw.y) * bfhi(rw.y));
;       ssq += (bflo(rw.z) * bflo(rw.z) + bfhi(rw.z) * bfhi(rw.z)) + (bflo(rw.w) * bflo(rw.w) + bfhi(rw.w) * bfhi(rw.w)); }
;     { auto rr = __builtin_amdgcn_permlane32_swap(__float_as_uint(ssq), __float_as_uint(ssq), false, false); ssq = __uint_as_float(rr[0]) + __uint_as_float(rr[1]); }
;     const float rsc = (SCALE * 1.4426950408889634f) / sqrtf(ssq * (1.f / 128.f) + EPS);
;     const int t = t0 + wid * QBLK + r32; const float frow = (float)(t >> 6), fcol = (float)(t & 63);
; #pragma unroll
;     for (int d0 = 0; d0 < 8; ++d0) { const v4u rw = *reinterpret_cast<const v4u*>(Qw + d0 * 16);
;       const f32x4 g0 = *reinterpret_cast<const f32x4*>(qg + 16 * d0 + 8 * hi), g1 = *reinterpret_cast<const f32x4*>(qg + 16 * d0 + 8 * hi + 4);
;       const float idx = d0 < 4 ? frow : fcol; v4u wv;
	v_and_b32_e32 v89, 0xffff0000, v87
	v_lshlrev_b32_e32 v90, 16, v86
	v_mul_f32_e32 v10, 0xbed49a78, v10
	v_mul_f32_e32 v9, v9, v8
	v_exp_f32_e32 v10, v10
	v_mul_f32_e32 v11, 0.15915494, v9
	v_floor_f32_e32 v11, v11
	v_fma_f32 v9, v9, 0.15915494, -v11
	v_sin_f32_e32 v98, v9
	v_cos_f32_e32 v96, v9
	v_mul_f32_e32 v20, v10, v8
	global_load_dwordx4 v[8:11], v95, s[22:23] offset:272
	global_load_dwordx4 v[12:15], v95, s[22:23] offset:256
	v_mul_f32_e32 v21, 0.15915494, v20
	v_cvt_f32_i32_e32 v16, v16
	v_cvt_f32_i32_e32 v17, v17
	v_floor_f32_e32 v21, v21
	v_fma_f32 v20, v20, 0.15915494, -v21
	v_mul_f32_e32 v16, 0xbed49a78, v16
	v_exp_f32_e32 v16, v16
	v_mul_f32_e32 v17, 0xbed49a78, v17
	v_exp_f32_e32 v17, v17
	v_sin_f32_e32 v102, v20
	v_mul_f32_e32 v16, v16, v93
	v_cos_f32_e32 v104, v20
	v_mul_f32_e32 v20, 0.15915494, v16
	v_floor_f32_e32 v20, v20
	v_fma_f32 v16, v16, 0.15915494, -v20
	v_sin_f32_e32 v108, v16
	v_cos_f32_e32 v106, v16
	v_mul_f32_e32 v16, v17, v93
	v_mul_f32_e32 v17, 0.15915494, v16
	v_cvt_f32_i32_e32 v18, v18
	v_floor_f32_e32 v17, v17
	v_fma_f32 v16, v16, 0.15915494, -v17
	v_sin_f32_e32 v130, v16
	v_cos_f32_e32 v132, v16
	v_mul_f32_e32 v17, 0xbed49a78, v18
	v_cvt_f32_i32_e32 v16, v19
	v_exp_f32_e32 v17, v17
	global_load_dwordx4 v[20:23], v95, s[22:23] offset:336
	global_load_dwordx4 v[28:31], v95, s[22:23] offset:320
	v_mul_f32_e32 v16, 0xbed49a78, v16
	v_exp_f32_e32 v16, v16
	v_mul_f32_e32 v17, v17, v93
	v_mul_f32_e32 v18, 0.15915494, v17
	v_floor_f32_e32 v18, v18
	v_fma_f32 v17, v17, 0.15915494, -v18
	v_mul_f32_e32 v16, v16, v93
	v_sin_f32_e32 v142, v17
	v_cos_f32_e32 v138, v17
	v_mul_f32_e32 v17, 0.15915494, v16
	v_cvt_f32_i32_e32 v18, v24
	v_floor_f32_e32 v17, v17
	v_fma_f32 v16, v16, 0.15915494, -v17
	v_sin_f32_e32 v144, v16
	v_cos_f32_e32 v146, v16
	v_mul_f32_e32 v17, 0xbed49a78, v18
	v_cvt_f32_i32_e32 v16, v25
	v_exp_f32_e32 v17, v17
	v_mul_f32_e32 v16, 0xbed49a78, v16
	v_exp_f32_e32 v16, v16
	v_mul_f32_e32 v17, v17, v93
	v_mul_f32_e32 v18, 0.15915494, v17
	v_floor_f32_e32 v18, v18
	v_fma_f32 v17, v17, 0.15915494, -v18
	v_mul_f32_e32 v16, v16, v93
	v_sin_f32_e32 v150, v17
	v_cos_f32_e32 v148, v17
	v_mul_f32_e32 v17, 0.15915494, v16
	v_cvt_f32_i32_e32 v18, v26
	v_floor_f32_e32 v17, v17
	v_fma_f32 v16, v16, 0.15915494, -v17
	v_sin_f32_e32 v110, v16
	v_cos_f32_e32 v134, v16
	v_cvt_f32_i32_e32 v16, v27
	v_mul_f32_e32 v17, 0xbed49a78, v18
	v_exp_f32_e32 v17, v17
	v_and_b32_e32 v91, 0xffff0000, v86
	v_mul_f32_e32 v16, 0xbed49a78, v16
	v_exp_f32_e32 v16, v16
	v_mul_f32_e32 v17, v17, v93
	v_mul_f32_e32 v18, 0.15915494, v17
	v_floor_f32_e32 v18, v18
	v_fma_f32 v17, v17, 0.15915494, -v18
	v_mul_f32_e32 v16, v16, v93
	v_sin_f32_e32 v140, v17
	v_cos_f32_e32 v136, v17
	v_mul_f32_e32 v17, 0.15915494, v16
	v_floor_f32_e32 v17, v17
	v_fma_f32 v113, v16, 0.15915494, -v17
	global_load_dwordx4 v[16:19], v95, s[22:23] offset:400
	global_load_dwordx4 v[24:27], v95, s[22:23] offset:384
	v_lshlrev_b32_e32 v86, 16, v85
	v_cvt_f32_i32_e32 v115, v88
	v_lshlrev_b32_e32 v88, 16, v87
	v_and_b32_e32 v87, 0xffff0000, v85
	v_and_b32_e32 v85, 0xffff0000, v83
	v_and_b32_e32 v153, 0xffff0000, v82
	v_lshlrev_b32_e32 v100, 16, v84
	v_and_b32_e32 v101, 0xffff0000, v84
	v_lshlrev_b32_e32 v84, 16, v83
	v_lshlrev_b32_e32 v152, 16, v82
	v_mov_b32_e32 v154, v153
	v_mov_b32_e32 v155, v85
	v_mov_b32_e32 v82, v152
	v_mov_b32_e32 v83, v84
	v_pk_mul_f32 v[154:155], v[154:155], v[154:155]
	v_and_b32_e32 v197, 0xffff0000, v76
	v_pk_fma_f32 v[212:213], v[82:83], v[82:83], v[154:155]
	v_lshlrev_b32_e32 v82, 16, v81
	v_and_b32_e32 v83, 0xffff0000, v81
	v_lshlrev_b32_e32 v154, 16, v80
	v_and_b32_e32 v155, 0xffff0000, v80
	v_lshlrev_b32_e32 v80, 16, v79
	v_and_b32_e32 v81, 0xffff0000, v79
	v_and_b32_e32 v79, 0xffff0000, v77
	v_lshlrev_b32_e32 v182, 16, v78
	v_and_b32_e32 v183, 0xffff0000, v78
	v_lshlrev_b32_e32 v78, 16, v77
	v_lshlrev_b32_e32 v196, 16, v76
	v_mov_b32_e32 v198, v197
	v_mov_b32_e32 v199, v79
	v_mov_b32_e32 v76, v196
	v_mov_b32_e32 v77, v78
	v_pk_mul_f32 v[198:199], v[198:199], v[198:199]
	v_and_b32_e32 v203, 0xffff0000, v70
	v_pk_fma_f32 v[214:215], v[76:77], v[76:77], v[198:199]
	v_lshlrev_b32_e32 v76, 16, v75
	v_and_b32_e32 v77, 0xffff0000, v75
	v_lshlrev_b32_e32 v198, 16, v74
	v_and_b32_e32 v199, 0xffff0000, v74
	v_lshlrev_b32_e32 v74, 16, v73
	v_and_b32_e32 v75, 0xffff0000, v73
	v_and_b32_e32 v73, 0xffff0000, v71
	v_lshlrev_b32_e32 v200, 16, v72
	v_and_b32_e32 v201, 0xffff0000, v72
	v_lshlrev_b32_e32 v72, 16, v71
	v_lshlrev_b32_e32 v202, 16, v70
	v_mov_b32_e32 v204, v203
	v_mov_b32_e32 v205, v73
	v_and_b32_e32 v245, 0xffff0000, v59
	v_and_b32_e32 v219, 0xffff0000, v58
	v_mov_b32_e32 v70, v202
	v_mov_b32_e32 v71, v72
	v_pk_mul_f32 v[204:205], v[204:205], v[204:205]
	v_lshlrev_b32_e32 v240, 16, v61
	v_and_b32_e32 v241, 0xffff0000, v61
	v_lshlrev_b32_e32 v242, 16, v60
	v_and_b32_e32 v243, 0xffff0000, v60
	v_lshlrev_b32_e32 v244, 16, v59
	v_lshlrev_b32_e32 v218, 16, v58
	v_mov_b32_e32 v60, v219
	v_mov_b32_e32 v61, v245
	v_pk_fma_f32 v[210:211], v[70:71], v[70:71], v[204:205]
	v_lshlrev_b32_e32 v70, 16, v69
	v_and_b32_e32 v71, 0xffff0000, v69
	v_lshlrev_b32_e32 v232, 16, v68
	v_and_b32_e32 v233, 0xffff0000, v68
	v_lshlrev_b32_e32 v68, 16, v67
	v_and_b32_e32 v69, 0xffff0000, v67
	v_and_b32_e32 v67, 0xffff0000, v65
	v_and_b32_e32 v237, 0xffff0000, v64
	v_mov_b32_e32 v58, v218
	v_mov_b32_e32 v59, v244
	v_pk_mul_f32 v[60:61], v[60:61], v[60:61]
	v_and_b32_e32 v221, 0xffff0000, v57
	v_and_b32_e32 v223, 0xffff0000, v56
	v_lshlrev_b32_e32 v234, 16, v66
	v_and_b32_e32 v235, 0xffff0000, v66
	v_lshlrev_b32_e32 v66, 16, v65
	v_lshlrev_b32_e32 v236, 16, v64
; __device__ __forceinline__ float bflo(unsigned w) { return __uint_as_float(w << 16); }
; __device__ __forceinline__ float bfhi(unsigned w) { return __uint_as_float(w & 0xffff0000u); }
; __device__ __forceinline__ void attn_unit_fast(const bf16* __restrict__ Qb, const bf16* __restrict__ Kh, const bf16* __restrict__ Vh, bf16* __restrict__ Ob, int NT, char* lds, int t0, const float* __restrict__ qg) {
;     ...
;     float ssq = 0.f;
; #pragma unroll
;     for (int d0 = 0; d0 < 8; ++d0) { const v4u rw = *reinterpret_cast<const v4u*>(Qw + d0 * 16);
;       ssq += (bflo(rw.x) * bflo(rw.x) + bfhi(rw.x) * bfhi(rw.x)) + (bflo(rw.y) * bflo(rw.y) + bfhi(rw.y) * bfhi(rw.y));
;       ssq += (bflo(rw.z) * bflo(rw.z) + bfhi(rw.z) * bfhi(rw.z)) + (bflo(rw.w) * bflo(rw.w) + bfhi(rw.w) * bfhi(rw.w)); }
;     { auto rr = __builtin_amdgcn_permlane32_swap(__float_as_uint(ssq), __float_as_uint(ssq), false, false); ssq = __uint_as_float(rr[0]) + __uint_as_float(rr[1]); }
;     const float rsc = (SCALE * 1.4426950408889634f) / sqrtf(ssq * (1.f / 128.f) + EPS);
;     const int t = t0 + wid * QBLK + r32; const float frow = (float)(t >> 6), fcol = (float)(t & 63);
; #pragma unroll
;     for (int d0 = 0; d0 < 8; ++d0) { const v4u rw = *reinterpret_cast<const v4u*>(Qw + d0 * 16);
;       const f32x4 g0 = *reinterpret_cast<const f32x4*>(qg + 16 * d0 + 8 * hi), g1 = *reinterpret_cast<const f32x4*>(qg + 16 * d0 + 8 * hi + 4);
;       const float idx = d0 < 4 ? frow : fcol; v4u wv;
	v_mov_b32_e32 v204, v237
	v_mov_b32_e32 v205, v67
	v_pk_fma_f32 v[58:59], v[58:59], v[58:59], v[60:61]
	v_lshlrev_b32_e32 v220, 16, v57
	v_lshlrev_b32_e32 v222, 16, v56
	v_mov_b32_e32 v60, v223
	v_mov_b32_e32 v61, v221
	v_mov_b32_e32 v64, v236
	v_mov_b32_e32 v65, v66
	v_pk_mul_f32 v[204:205], v[204:205], v[204:205]
	v_mov_b32_e32 v56, v222
	v_mov_b32_e32 v57, v220
	v_pk_mul_f32 v[60:61], v[60:61], v[60:61]
	v_pk_fma_f32 v[206:207], v[64:65], v[64:65], v[204:205]
	v_lshlrev_b32_e32 v64, 16, v63
	v_and_b32_e32 v65, 0xffff0000, v63
	v_lshlrev_b32_e32 v238, 16, v62
	v_and_b32_e32 v239, 0xffff0000, v62
	v_mul_f32_e32 v62, v240, v240
	v_pk_fma_f32 v[56:57], v[56:57], v[56:57], v[60:61]
	v_mul_f32_e32 v60, v242, v242
	v_pk_mul_f32 v[204:205], v[64:65], v[64:65]
	v_pk_fma_f32 v[62:63], v[240:241], v[240:241], v[62:63] op_sel_hi:[1,1,0]
	v_pk_fma_f32 v[208:209], v[242:243], v[242:243], v[60:61] op_sel_hi:[1,1,0]
	v_mov_b32_e32 v62, v205
	v_mov_b32_e32 v208, v204
	v_pk_mul_f32 v[204:205], v[238:239], v[238:239]
	v_pk_add_f32 v[58:59], v[58:59], v[58:59] op_sel_hi:[0,1]
	v_pk_add_f32 v[56:57], v[56:57], v[56:57] op_sel_hi:[0,1]
	v_mov_b32_e32 v58, v204
	v_mov_b32_e32 v56, v205
	v_pk_add_f32 v[56:57], v[58:59], v[56:57]
	v_mul_f32_e32 v58, v68, v68
	v_pk_fma_f32 v[58:59], v[68:69], v[68:69], v[58:59] op_sel_hi:[1,1,0]
	v_cvt_f32_i32_e32 v111, v111
	v_pk_add_f32 v[62:63], v[208:209], v[62:63]
	v_mul_f32_e32 v58, v234, v234
	v_pk_mul_f32 v[204:205], v[232:233], v[232:233]
	v_pk_add_f32 v[56:57], v[56:57], v[62:63]
	v_pk_fma_f32 v[62:63], v[234:235], v[234:235], v[58:59] op_sel_hi:[1,1,0]
	v_mul_f32_e32 v61, 0xbed49a78, v115
	v_mov_b32_e32 v62, v204
	v_mov_b32_e32 v58, v205
	v_exp_f32_e32 v61, v61
	v_mul_f32_e32 v111, 0xbed49a78, v111
	v_pk_add_f32 v[58:59], v[62:63], v[58:59]
	v_pk_mul_f32 v[62:63], v[70:71], v[70:71]
	v_pk_add_f32 v[206:207], v[206:207], v[206:207] op_sel_hi:[0,1]
	v_pk_add_f32 v[56:57], v[56:57], v[56:57] op_sel_hi:[0,1]
	v_exp_f32_e32 v111, v111
	v_mov_b32_e32 v206, v62
	v_mov_b32_e32 v56, v63
	v_pk_add_f32 v[56:57], v[206:207], v[56:57]
	v_mul_f32_e32 v61, v61, v93
	v_pk_add_f32 v[56:57], v[58:59], v[56:57]
	v_mul_f32_e32 v58, v200, v200
	v_pk_mul_f32 v[62:63], v[198:199], v[198:199]
	v_mul_f32_e32 v206, v74, v74
	v_pk_fma_f32 v[58:59], v[200:201], v[200:201], v[58:59] op_sel_hi:[1,1,0]
	v_sin_f32_e32 v60, v113
	v_cos_f32_e32 v204, v113
	v_mul_f32_e32 v113, 0.15915494, v61
	v_pk_fma_f32 v[216:217], v[74:75], v[74:75], v[206:207] op_sel_hi:[1,1,0]
	v_mov_b32_e32 v58, v62
	v_mul_f32_e32 v62, v111, v93
	v_floor_f32_e32 v113, v113
	v_mov_b32_e32 v216, v63
	v_mul_f32_e32 v63, 0.15915494, v62
	v_fma_f32 v61, v61, 0.15915494, -v113
	v_floor_f32_e32 v63, v63
	v_sin_f32_e32 v208, v61
	v_fma_f32 v111, v62, 0.15915494, -v63
	v_cos_f32_e32 v206, v61
	v_pk_mul_f32 v[62:63], v[76:77], v[76:77]
	v_cvt_f32_i32_e32 v61, v109
	v_pk_add_f32 v[210:211], v[210:211], v[210:211] op_sel_hi:[0,1]
	v_pk_add_f32 v[56:57], v[56:57], v[56:57] op_sel_hi:[0,1]
	v_mov_b32_e32 v210, v62
	v_mov_b32_e32 v56, v63
	v_pk_add_f32 v[58:59], v[58:59], v[216:217]
	v_pk_add_f32 v[56:57], v[210:211], v[56:57]
	v_mul_f32_e32 v210, v80, v80
	v_pk_add_f32 v[56:57], v[58:59], v[56:57]
	v_mul_f32_e32 v58, v182, v182
	v_pk_mul_f32 v[62:63], v[154:155], v[154:155]
	v_pk_fma_f32 v[216:217], v[80:81], v[80:81], v[210:211] op_sel_hi:[1,1,0]
	v_pk_fma_f32 v[58:59], v[182:183], v[182:183], v[58:59] op_sel_hi:[1,1,0]
	v_mul_f32_e32 v61, 0xbed49a78, v61
	v_mov_b32_e32 v58, v62
	v_mov_b32_e32 v216, v63
	v_exp_f32_e32 v61, v61
	v_pk_mul_f32 v[62:63], v[82:83], v[82:83]
	v_pk_add_f32 v[214:215], v[214:215], v[214:215] op_sel_hi:[0,1]
	v_pk_add_f32 v[56:57], v[56:57], v[56:57] op_sel_hi:[0,1]
	v_mov_b32_e32 v214, v62
	v_mov_b32_e32 v56, v63
	v_pk_add_f32 v[58:59], v[58:59], v[216:217]
	v_pk_add_f32 v[56:57], v[214:215], v[56:57]
	v_pk_mul_f32 v[62:63], v[90:91], v[90:91]
	v_pk_add_f32 v[56:57], v[58:59], v[56:57]
	v_mul_f32_e32 v58, v100, v100
	v_mul_f32_e32 v214, v86, v86
	v_pk_fma_f32 v[58:59], v[100:101], v[100:101], v[58:59] op_sel_hi:[1,1,0]
	v_mul_f32_e32 v61, v61, v93
	v_pk_fma_f32 v[214:215], v[86:87], v[86:87], v[214:215] op_sel_hi:[1,1,0]
	v_mov_b32_e32 v58, v62
	v_mul_f32_e32 v62, 0.15915494, v61
	v_mov_b32_e32 v214, v63
	v_floor_f32_e32 v109, v62
	v_pk_mul_f32 v[62:63], v[88:89], v[88:89]
	v_pk_add_f32 v[212:213], v[212:213], v[212:213] op_sel_hi:[0,1]
	v_pk_add_f32 v[56:57], v[56:57], v[56:57] op_sel_hi:[0,1]
	v_mov_b32_e32 v212, v62
	v_mov_b32_e32 v56, v63
	v_pk_add_f32 v[58:59], v[58:59], v[214:215]
	v_pk_add_f32 v[56:57], v[212:213], v[56:57]
	s_add_u32 s44, s16, s0
	v_pk_add_f32 v[56:57], v[58:59], v[56:57]
	v_fma_f32 v58, v61, 0.15915494, -v109
	v_pk_add_f32 v[56:57], v[56:57], v[56:57] op_sel:[0,1] op_sel_hi:[1,0]
	v_cvt_f32_i32_e32 v107, v107
	v_mov_b32_e32 v57, v56
	s_nop 1
	v_permlane32_swap_b32_e32 v56, v57
	v_add_f32_e32 v56, v56, v57
	v_fmamk_f32 v56, v56, 0x3c000000, v185
	v_mul_f32_e32 v57, 0x4f800000, v56
	v_cmp_gt_f32_e32 vcc, s89, v56
	v_mul_f32_e32 v59, 0xbed49a78, v107
	v_exp_f32_e32 v59, v59
	v_cndmask_b32_e32 v56, v56, v57, vcc
	v_sqrt_f32_e32 v57, v56
	v_sin_f32_e32 v230, v58
	v_cos_f32_e32 v228, v58
	v_mul_f32_e32 v63, v59, v93
	v_add_u32_e32 v61, -1, v57
	v_fma_f32 v62, -v61, v57, v56
	v_cmp_ge_f32_e64 s[4:5], 0, v62
	v_add_u32_e32 v62, 1, v57
	s_addc_u32 s45, s17, s1
	v_cndmask_b32_e64 v61, v57, v61, s[4:5]
	v_fma_f32 v57, -v62, v57, v56
	v_cmp_lt_f32_e64 s[4:5], 0, v57
	s_add_u32 s66, s18, s0
	s_addc_u32 s67, s19, s1
	v_cndmask_b32_e64 v57, v61, v62, s[4:5]
	v_mul_f32_e32 v61, 0x37800000, v57
	v_cndmask_b32_e32 v57, v57, v61, vcc
	v_cmp_class_f32_e32 vcc, v56, v187
; #define QROPE(RW, GA, GB, E2, OUT) do { int pp = (8 * d0 + 4 * hi + (E2)) & 31; asm volatile("" : "+v"(pp)); const float freq = __builtin_amdgcn_exp2f(-(float)pp * (13.287712379549449f / 32.f)); \
;         float sn, cs; sincos_rev(idx * freq * INV2PI, sn, cs); const float y0 = bflo(RW) * rsc * (GA), y1 = bfhi(RW) * rsc * (GB); OUT = cvtpk(y0 * cs - y1 * sn, y0 * sn + y1 * cs); } while (0)
; __device__ __forceinline__ void attn_unit_fast(const bf16* __restrict__ Qb, const bf16* __restrict__ Kh, const bf16* __restrict__ Vh, bf16* __restrict__ Ob, int NT, char* lds, int t0, const float* __restrict__ qg) {
;     ...
;     const float rsc = (SCALE * 1.4426950408889634f) / sqrtf(ssq * (1.f / 128.f) + EPS);
;     const int t = t0 + wid * QBLK + r32; const float frow = (float)(t >> 6), fcol = (float)(t & 63);
; #pragma unroll
;     for (int d0 = 0; d0 < 8; ++d0) { const v4u rw = *reinterpret_cast<const v4u*>(Qw + d0 * 16);
;       const f32x4 g0 = *reinterpret_cast<const f32x4*>(qg + 16 * d0 + 8 * hi), g1 = *reinterpret_cast<const f32x4*>(qg + 16 * d0 + 8 * hi + 4);
;       const float idx = d0 < 4 ? frow : fcol; v4u wv;
;     ...
;       QROPE(rw.x, g0.x, g0.y, 0, wv.x); QROPE(rw.y, g0.z, g0.w, 1, wv.y); QROPE(rw.z, g1.x, g1.y, 2, wv.z); QROPE(rw.w, g1.z, g1.w, 3, wv.w);
;     ...
;       qr[d0] = __builtin_bit_cast(bf16x8, wv); }
	v_sin_f32_e32 v210, v111
	v_cos_f32_e32 v216, v111
	v_cndmask_b32_e32 v56, v57, v56, vcc
	v_div_scale_f32 v57, s[4:5], v56, v56, s72
	v_rcp_f32_e32 v61, v57
	v_and_b32_e32 v179, 63, v195
	s_cmp_lg_u32 0, -1
	s_cselect_b32 s4, 0, 0
	v_fma_f32 v58, -v57, v61, 1.0
	v_fmac_f32_e32 v61, v58, v61
	v_div_scale_f32 v58, vcc, s72, v56, s72
	v_mul_f32_e32 v59, v58, v61
	v_fma_f32 v62, -v57, v59, v58
	v_fmac_f32_e32 v59, v62, v61
	v_fma_f32 v57, -v57, v59, v58
	v_div_fmas_f32 v57, v57, v61, v59
	v_div_fixup_f32 v62, v57, v56, s72
	v_pk_mul_f32 v[56:57], v[62:63], v[222:223] op_sel_hi:[0,1]
	v_pk_mul_f32 v[48:49], v[48:49], v[56:57]
	s_mov_b32 s20, 4
	v_pk_mul_f32 v[56:57], v[48:49], v[164:165] op_sel:[1,0] op_sel_hi:[0,0]
	v_pk_fma_f32 v[222:223], v[48:49], v[160:161], v[56:57] neg_lo:[0,0,1] neg_hi:[0,0,1]
	v_pk_fma_f32 v[160:161], v[48:49], v[160:161], v[56:57] op_sel_hi:[1,0,1]
	v_pk_mul_f32 v[48:49], v[62:63], v[220:221] op_sel_hi:[0,1]
	v_pk_mul_f32 v[164:165], v[50:51], v[48:49]
	global_load_dwordx4 v[48:51], v95, s[22:23] offset:464
	global_load_dwordx4 v[56:59], v95, s[22:23] offset:448
	v_mul_f32_e32 v95, 0.15915494, v63
	v_cvt_f32_i32_e32 v61, v99
	v_floor_f32_e32 v95, v95
	v_fma_f32 v63, v63, 0.15915494, -v95
	v_mul_f32_e32 v61, 0xbed49a78, v61
	v_exp_f32_e32 v61, v61
	v_cvt_f32_i32_e32 v95, v97
	v_pk_mul_f32 v[156:157], v[164:165], v[156:157] op_sel:[1,0] op_sel_hi:[0,0]
	v_pk_fma_f32 v[220:221], v[164:165], v[112:113], v[156:157] neg_lo:[0,0,1] neg_hi:[0,0,1]
	v_mul_f32_e32 v61, v61, v93
	v_pk_fma_f32 v[112:113], v[164:165], v[112:113], v[156:157] op_sel_hi:[1,0,1]
	v_sin_f32_e32 v212, v63
	v_cos_f32_e32 v164, v63
	v_mul_f32_e32 v63, 0.15915494, v61
	v_floor_f32_e32 v63, v63
	v_fma_f32 v61, v61, 0.15915494, -v63
	v_mul_f32_e32 v63, 0xbed49a78, v95
	v_exp_f32_e32 v63, v63
	v_sin_f32_e32 v214, v61
	v_cos_f32_e32 v160, v61
	v_mul_f32_e32 v61, v63, v93
	v_mul_f32_e32 v63, 0.15915494, v61
	v_floor_f32_e32 v63, v63
	v_fma_f32 v61, v61, 0.15915494, -v63
	v_cvt_f32_i32_e32 v63, v103
	v_cvt_pk_bf16_f32 v112, v222, v161
	v_sin_f32_e32 v222, v61
	v_pk_mul_f32 v[156:157], v[62:63], v[218:219] op_sel_hi:[0,1]
	v_pk_mul_f32 v[32:33], v[32:33], v[156:157]
	v_cos_f32_e32 v224, v61
	v_pk_mul_f32 v[126:127], v[32:33], v[126:127] op_sel:[1,0] op_sel_hi:[0,0]
	v_pk_fma_f32 v[156:157], v[32:33], v[114:115], v[126:127] neg_lo:[0,0,1] neg_hi:[0,0,1]
	v_pk_fma_f32 v[32:33], v[32:33], v[114:115], v[126:127] op_sel_hi:[1,0,1]
	v_cvt_pk_bf16_f32 v113, v220, v113
	v_mul_f32_e32 v32, 0xbed49a78, v63
	v_cvt_f32_i32_e32 v63, v105
	v_exp_f32_e32 v32, v32
	v_cvt_pk_bf16_f32 v114, v156, v33
	v_lshlrev_b32_e32 v33, 3, v195
	v_mul_f32_e32 v63, 0xbed49a78, v63
	v_exp_f32_e32 v63, v63
	v_mul_f32_e32 v32, v32, v93
	v_mul_f32_e32 v61, 0.15915494, v32
	v_floor_f32_e32 v61, v61
	v_fma_f32 v32, v32, 0.15915494, -v61
	v_mul_f32_e32 v61, v63, v93
	v_mul_f32_e32 v63, 0.15915494, v61
	v_floor_f32_e32 v63, v63
	v_pk_mul_f32 v[126:127], v[62:63], v[244:245] op_sel_hi:[0,1]
	v_pk_mul_f32 v[34:35], v[34:35], v[126:127]
	v_fma_f32 v61, v61, 0.15915494, -v63
	v_pk_mul_f32 v[118:119], v[34:35], v[118:119] op_sel:[1,0] op_sel_hi:[0,0]
	v_pk_fma_f32 v[126:127], v[34:35], v[116:117], v[118:119] neg_lo:[0,0,1] neg_hi:[0,0,1]
	v_pk_fma_f32 v[34:35], v[34:35], v[116:117], v[118:119] op_sel_hi:[1,0,1]
	v_sin_f32_e32 v220, v32
	v_cvt_pk_bf16_f32 v115, v126, v35
	v_pk_mul_f32 v[34:35], v[62:63], v[242:243] op_sel_hi:[0,1]
	v_pk_mul_f32 v[34:35], v[40:41], v[34:35]
	v_cos_f32_e32 v226, v32
	v_pk_mul_f32 v[40:41], v[34:35], v[122:123] op_sel:[1,0] op_sel_hi:[0,0]
	v_pk_fma_f32 v[116:117], v[34:35], v[120:121], v[40:41] neg_lo:[0,0,1] neg_hi:[0,0,1]
	v_pk_fma_f32 v[34:35], v[34:35], v[120:121], v[40:41] op_sel_hi:[1,0,1]
	v_sin_f32_e32 v218, v61
	v_cvt_pk_bf16_f32 v116, v116, v35
	v_pk_mul_f32 v[34:35], v[62:63], v[240:241] op_sel_hi:[0,1]
	v_pk_mul_f32 v[34:35], v[42:43], v[34:35]
	v_cos_f32_e32 v32, v61
	v_pk_mul_f32 v[40:41], v[34:35], v[128:129] op_sel:[1,0] op_sel_hi:[0,0]
	v_pk_fma_f32 v[42:43], v[34:35], v[124:125], v[40:41] neg_lo:[0,0,1] neg_hi:[0,0,1]
	v_pk_fma_f32 v[34:35], v[34:35], v[124:125], v[40:41] op_sel_hi:[1,0,1]
	s_nop 0
	v_cvt_pk_bf16_f32 v117, v42, v35
	v_pk_mul_f32 v[34:35], v[62:63], v[238:239] op_sel_hi:[0,1]
	v_pk_mul_f32 v[34:35], v[34:35], v[36:37]
	s_nop 0
	v_pk_mul_f32 v[36:37], v[34:35], v[162:163] op_sel:[1,0] op_sel_hi:[0,0]
	v_pk_fma_f32 v[40:41], v[34:35], v[158:159], v[36:37] neg_lo:[0,0,1] neg_hi:[0,0,1]
	v_pk_fma_f32 v[34:35], v[34:35], v[158:159], v[36:37] op_sel_hi:[1,0,1]
	s_nop 0
	v_cvt_pk_bf16_f32 v118, v40, v35
	v_pk_mul_f32 v[34:35], v[62:63], v[64:65] op_sel_hi:[0,1]
	v_pk_mul_f32 v[34:35], v[34:35], v[38:39]
	s_nop 0
	v_pk_mul_f32 v[36:37], v[34:35], v[168:169] op_sel:[1,0] op_sel_hi:[0,0]
	v_pk_fma_f32 v[38:39], v[34:35], v[166:167], v[36:37] neg_lo:[0,0,1] neg_hi:[0,0,1]
	v_pk_fma_f32 v[34:35], v[34:35], v[166:167], v[36:37] op_sel_hi:[1,0,1]
	s_nop 0
	v_cvt_pk_bf16_f32 v119, v38, v35
	v_pk_mul_f32 v[34:35], v[62:63], v[236:237] op_sel_hi:[0,1]
	v_pk_mul_f32 v[34:35], v[34:35], v[52:53]
	s_nop 0
	v_pk_mul_f32 v[36:37], v[34:35], v[172:173] op_sel:[1,0] op_sel_hi:[0,0]
	v_pk_fma_f32 v[38:39], v[34:35], v[170:171], v[36:37] neg_lo:[0,0,1] neg_hi:[0,0,1]
	v_pk_fma_f32 v[34:35], v[34:35], v[170:171], v[36:37] op_sel_hi:[1,0,1]
	s_nop 0
	v_cvt_pk_bf16_f32 v120, v38, v35
	v_pk_mul_f32 v[34:35], v[62:63], v[66:67] op_sel_hi:[0,1]
	v_pk_mul_f32 v[34:35], v[34:35], v[54:55]
	s_nop 0
	v_pk_mul_f32 v[36:37], v[34:35], v[180:181] op_sel:[1,0] op_sel_hi:[0,0]
	v_pk_fma_f32 v[38:39], v[34:35], v[174:175], v[36:37] neg_lo:[0,0,1] neg_hi:[0,0,1]
; __device__ __forceinline__ int v_st(int k, int c) { const int kk = (k & ~0xC) | ((k & 4) << 1) | ((k & 8) >> 1); return ((kk >> 3) * 4 + (c >> 5)) * 512 + ((kk & 7) * 32 + (c & 31)) * 2; }
; __device__ __forceinline__ int v_rd_base(int lane) { return ((lane & 3) << 3) | (((lane >> 2) & 3) << 6) | (((lane >> 4) & 1) << 5) | (((lane >> 5) & 1) << 8); }
; #define QROPE(RW, GA, GB, E2, OUT) do { int pp = (8 * d0 + 4 * hi + (E2)) & 31; asm volatile("" : "+v"(pp)); const float freq = __builtin_amdgcn_exp2f(-(float)pp * (13.287712379549449f / 32.f)); \
;         float sn, cs; sincos_rev(idx * freq * INV2PI, sn, cs); const float y0 = bflo(RW) * rsc * (GA), y1 = bfhi(RW) * rsc * (GB); OUT = cvtpk(y0 * cs - y1 * sn, y0 * sn + y1 * cs); } while (0)
; #define SLOAD(i, k0) do { sr_[i].vs0 = *reinterpret_cast<const bf16x8*>(&Vh[(long)((k0) + sr) * LDK + sc]); sr_[i].vs1 = *reinterpret_cast<const bf16x8*>(&Vh[(long)((k0) + 32 + sr) * LDK + sc]); \
;     sr_[i].ks0 = *reinterpret_cast<const bf16x8*>(&Kh[(long)((k0) + sr) * LDK + sc]); sr_[i].ks1 = *reinterpret_cast<const bf16x8*>(&Kh[(long)((k0) + 32 + sr) * LDK + sc]); } while (0)
; __device__ __forceinline__ void attn_unit_fast(const bf16* __restrict__ Qb, const bf16* __restrict__ Kh, const bf16* __restrict__ Vh, bf16* __restrict__ Ob, int NT, char* lds, int t0, const float* __restrict__ qg) {
;     ...
;     for (int d0 = 0; d0 < 8; ++d0) { const v4u rw = *reinterpret_cast<const v4u*>(Qw + d0 * 16);
;       const f32x4 g0 = *reinterpret_cast<const f32x4*>(qg + 16 * d0 + 8 * hi), g1 = *reinterpret_cast<const f32x4*>(qg + 16 * d0 + 8 * hi + 4);
;       const float idx = d0 < 4 ? frow : fcol; v4u wv;
;     ...
;       QROPE(rw.x, g0.x, g0.y, 0, wv.x); QROPE(rw.y, g0.z, g0.w, 1, wv.y); QROPE(rw.z, g1.x, g1.y, 2, wv.z); QROPE(rw.w, g1.z, g1.w, 3, wv.w);
;     ...
;       qr[d0] = __builtin_bit_cast(bf16x8, wv); }
;     ...
;   const int sr = tid >> 4, sc = (tid & 15) * 8, vst0 = v_st(sr, sc), vst1 = v_st(32 + sr, sc);
;   const int vb0 = (int)(uintptr_t)V_lds + v_rd_base(lane);
;   struct { bf16x8 vs0, vs1, ks0, ks1; } sr_[2];
;     ...
;   f32x16 pA0, pA1, pB0, pB1; bf16x8 pa0, pa1, pa2, pa3;
;   constexpr int SE = 0, SO = 1;
;   SLOAD(SE, 0); asm volatile("s_waitcnt vmcnt(0)" ::: "memory"); SWRITE(0, SE); __syncthreads();
	v_pk_fma_f32 v[34:35], v[34:35], v[174:175], v[36:37] op_sel_hi:[1,0,1]
	s_nop 0
	v_cvt_pk_bf16_f32 v121, v38, v35
	v_pk_mul_f32 v[34:35], v[62:63], v[234:235] op_sel_hi:[0,1]
	v_pk_mul_f32 v[34:35], v[34:35], v[44:45]
	s_nop 0
	v_pk_mul_f32 v[36:37], v[34:35], v[186:187] op_sel:[1,0] op_sel_hi:[0,0]
	v_pk_fma_f32 v[38:39], v[34:35], v[184:185], v[36:37] neg_lo:[0,0,1] neg_hi:[0,0,1]
	v_pk_fma_f32 v[34:35], v[34:35], v[184:185], v[36:37] op_sel_hi:[1,0,1]
	s_nop 0
	v_cvt_pk_bf16_f32 v122, v38, v35
	v_pk_mul_f32 v[34:35], v[62:63], v[68:69] op_sel_hi:[0,1]
	v_pk_mul_f32 v[34:35], v[34:35], v[46:47]
	v_ashrrev_i32_e32 v46, 4, v195
	v_pk_mul_f32 v[36:37], v[34:35], v[190:191] op_sel:[1,0] op_sel_hi:[0,0]
	v_pk_fma_f32 v[38:39], v[34:35], v[188:189], v[36:37] neg_lo:[0,0,1] neg_hi:[0,0,1]
	v_pk_fma_f32 v[34:35], v[34:35], v[188:189], v[36:37] op_sel_hi:[1,0,1]
	v_add_u32_e32 v64, 32, v46
	v_cvt_pk_bf16_f32 v123, v38, v35
	v_pk_mul_f32 v[34:35], v[62:63], v[232:233] op_sel_hi:[0,1]
	v_pk_mul_f32 v[4:5], v[34:35], v[4:5]
	v_ashrrev_i32_e32 v47, 31, v46
	v_pk_mul_f32 v[34:35], v[4:5], v[194:195] op_sel:[1,0] op_sel_hi:[0,0]
	v_pk_fma_f32 v[36:37], v[4:5], v[192:193], v[34:35] neg_lo:[0,0,1] neg_hi:[0,0,1]
	v_pk_fma_f32 v[4:5], v[4:5], v[192:193], v[34:35] op_sel_hi:[1,0,1]
	v_lshlrev_b64 v[34:35], 8, v[46:47]
	v_and_b32_e32 v4, 0x78, v33
	v_lshlrev_b32_e32 v61, 1, v4
	v_ashrrev_i32_e32 v65, 31, v64
	v_cvt_pk_bf16_f32 v124, v36, v5
	v_or_b32_e32 v36, v34, v61
	v_mov_b32_e32 v37, v35
	v_lshlrev_b64 v[52:53], 8, v[64:65]
	v_lshl_add_u64 v[4:5], s[66:67], 0, v[36:37]
	v_or_b32_e32 v52, v52, v61
	global_load_dwordx4 v[38:41], v[4:5], off
	v_lshl_add_u64 v[4:5], s[66:67], 0, v[52:53]
	global_load_dwordx4 v[42:45], v[4:5], off
	v_pk_mul_f32 v[4:5], v[62:63], v[70:71] op_sel_hi:[0,1]
	v_pk_mul_f32 v[54:55], v[4:5], v[6:7]
	v_lshl_add_u64 v[4:5], s[44:45], 0, v[36:37]
	global_load_dwordx4 v[4:7], v[4:5], off
	v_pk_mul_f32 v[66:67], v[54:55], v[94:95] op_sel:[1,0] op_sel_hi:[0,0]
	v_lshl_add_u64 v[52:53], s[44:45], 0, v[52:53]
	v_pk_fma_f32 v[68:69], v[54:55], v[92:93], v[66:67] neg_lo:[0,0,1] neg_hi:[0,0,1]
	v_pk_fma_f32 v[66:67], v[54:55], v[92:93], v[66:67] op_sel_hi:[1,0,1]
	global_load_dwordx4 v[52:55], v[52:53], off
	v_cvt_pk_bf16_f32 v125, v68, v67
	v_pk_mul_f32 v[66:67], v[62:63], v[202:203] op_sel_hi:[0,1]
	v_pk_mul_f32 v[0:1], v[66:67], v[0:1]
	s_waitcnt vmcnt(0)
	s_nop 0
	v_pk_mul_f32 v[66:67], v[0:1], v[98:99] op_sel:[1,0] op_sel_hi:[0,0]
	v_pk_fma_f32 v[68:69], v[0:1], v[96:97], v[66:67] neg_lo:[0,0,1] neg_hi:[0,0,1]
	v_pk_fma_f32 v[0:1], v[0:1], v[96:97], v[66:67] op_sel_hi:[1,0,1]
	s_nop 0
	v_cvt_pk_bf16_f32 v126, v68, v1
	v_pk_mul_f32 v[0:1], v[62:63], v[72:73] op_sel_hi:[0,1]
	v_pk_mul_f32 v[0:1], v[0:1], v[2:3]
	s_nop 0
	v_pk_mul_f32 v[2:3], v[0:1], v[102:103] op_sel:[1,0] op_sel_hi:[0,0]
	v_pk_fma_f32 v[66:67], v[0:1], v[104:105], v[2:3] neg_lo:[0,0,1] neg_hi:[0,0,1]
	v_pk_fma_f32 v[0:1], v[0:1], v[104:105], v[2:3] op_sel_hi:[1,0,1]
	s_nop 0
	v_cvt_pk_bf16_f32 v127, v66, v1
	v_pk_mul_f32 v[0:1], v[62:63], v[200:201] op_sel_hi:[0,1]
	s_waitcnt vmcnt(10)
	v_pk_mul_f32 v[0:1], v[0:1], v[12:13]
	s_nop 0
	v_pk_mul_f32 v[2:3], v[0:1], v[108:109] op_sel:[1,0] op_sel_hi:[0,0]
	v_pk_fma_f32 v[12:13], v[0:1], v[106:107], v[2:3] neg_lo:[0,0,1] neg_hi:[0,0,1]
	v_pk_fma_f32 v[0:1], v[0:1], v[106:107], v[2:3] op_sel_hi:[1,0,1]
	s_nop 0
	v_cvt_pk_bf16_f32 v128, v12, v1
	v_pk_mul_f32 v[0:1], v[62:63], v[74:75] op_sel_hi:[0,1]
	v_pk_mul_f32 v[0:1], v[0:1], v[14:15]
	s_nop 0
	v_pk_mul_f32 v[2:3], v[0:1], v[130:131] op_sel:[1,0] op_sel_hi:[0,0]
	v_pk_fma_f32 v[12:13], v[0:1], v[132:133], v[2:3] neg_lo:[0,0,1] neg_hi:[0,0,1]
	v_pk_fma_f32 v[0:1], v[0:1], v[132:133], v[2:3] op_sel_hi:[1,0,1]
	s_nop 0
	v_cvt_pk_bf16_f32 v129, v12, v1
	v_pk_mul_f32 v[0:1], v[62:63], v[198:199] op_sel_hi:[0,1]
	v_pk_mul_f32 v[0:1], v[0:1], v[8:9]
	s_nop 0
	v_pk_mul_f32 v[2:3], v[0:1], v[142:143] op_sel:[1,0] op_sel_hi:[0,0]
	v_pk_fma_f32 v[8:9], v[0:1], v[138:139], v[2:3] neg_lo:[0,0,1] neg_hi:[0,0,1]
	v_pk_fma_f32 v[0:1], v[0:1], v[138:139], v[2:3] op_sel_hi:[1,0,1]
	s_nop 0
	v_cvt_pk_bf16_f32 v130, v8, v1
	v_pk_mul_f32 v[0:1], v[62:63], v[76:77] op_sel_hi:[0,1]
	v_pk_mul_f32 v[0:1], v[0:1], v[10:11]
	v_and_b32_e32 v10, 0xfffff0, v64
	v_pk_mul_f32 v[2:3], v[0:1], v[144:145] op_sel:[1,0] op_sel_hi:[0,0]
	v_pk_fma_f32 v[8:9], v[0:1], v[146:147], v[2:3] neg_lo:[0,0,1] neg_hi:[0,0,1]
	v_pk_fma_f32 v[0:1], v[0:1], v[146:147], v[2:3] op_sel_hi:[1,0,1]
	v_lshlrev_b32_e32 v11, 1, v64
	v_cvt_pk_bf16_f32 v131, v8, v1
	v_pk_mul_f32 v[0:1], v[62:63], v[196:197] op_sel_hi:[0,1]
	s_waitcnt vmcnt(8)
	v_pk_mul_f32 v[0:1], v[0:1], v[28:29]
	v_and_or_b32 v10, v11, 8, v10
	v_pk_mul_f32 v[2:3], v[0:1], v[150:151] op_sel:[1,0] op_sel_hi:[0,0]
	v_pk_fma_f32 v[8:9], v[0:1], v[148:149], v[2:3] neg_lo:[0,0,1] neg_hi:[0,0,1]
	v_pk_fma_f32 v[0:1], v[0:1], v[148:149], v[2:3] op_sel_hi:[1,0,1]
	v_bfe_u32 v2, v33, 5, 2
	v_cvt_pk_bf16_f32 v132, v8, v1
	v_pk_mul_f32 v[0:1], v[62:63], v[78:79] op_sel_hi:[0,1]
	v_pk_mul_f32 v[8:9], v[0:1], v[30:31]
	v_and_b32_e32 v0, 0xfffff0, v46
	v_lshlrev_b32_e32 v1, 1, v46
	v_and_or_b32 v0, v1, 8, v0
	v_lshrrev_b32_e32 v1, 1, v46
	v_lshrrev_b32_e32 v0, 1, v0
	v_and_b32_e32 v3, 3, v46
	v_lshrrev_b32_e32 v10, 1, v10
	v_or_b32_e32 v0, v0, v2
	v_and_or_b32 v1, v1, 4, v3
	v_or_b32_e32 v2, v10, v2
	v_lshlrev_b32_e32 v0, 9, v0
	v_lshlrev_b32_e32 v1, 6, v1
	v_and_b32_e32 v3, 48, v61
	v_lshlrev_b32_e32 v2, 9, v2
	v_or3_b32 v0, v0, v1, v3
	v_or3_b32 v1, v2, v1, v3
	v_add_u32_e32 v184, 0, v0
	v_add_u32_e32 v186, 0, v1
	v_lshlrev_b32_e32 v0, 8, v46
	v_and_b32_e32 v1, 0x70, v195
	v_bitop3_b32 v0, v61, v0, v1 bitop3:0xde
	v_lshlrev_b32_e32 v33, 4, v195
	v_add_u32_e32 v190, 0x10800, v0
	v_lshlrev_b32_e32 v0, 8, v64
	s_waitcnt vmcnt(3)
	ds_write_b128 v184, v[38:41]
	s_waitcnt vmcnt(2)
	ds_write_b128 v186, v[42:45]
	v_bitop3_b32 v0, v61, v0, v1 bitop3:0xde
	v_lshlrev_b32_e32 v42, 8, v191
	v_and_b32_e32 v43, 0x70, v33
	s_waitcnt vmcnt(1)
	ds_write_b128 v190, v[4:7]
	v_add_u32_e32 v192, 0x10800, v0
	v_bitop3_b32 v0, v176, v42, v43 bitop3:0xde
	v_pk_mul_f32 v[4:5], v[8:9], v[110:111] op_sel:[1,0] op_sel_hi:[0,0]
	v_add_u32_e32 v194, 0x10800, v0
	v_pk_fma_f32 v[6:7], v[8:9], v[134:135], v[4:5] neg_lo:[0,0,1] neg_hi:[0,0,1]
	v_pk_fma_f32 v[4:5], v[8:9], v[134:135], v[4:5] op_sel_hi:[1,0,1]
	s_waitcnt vmcnt(0)
	ds_write_b128 v192, v[52:55]
	s_waitcnt lgkmcnt(0)
	s_barrier
; #define SLOAD(i, k0) do { sr_[i].vs0 = *reinterpret_cast<const bf16x8*>(&Vh[(long)((k0) + sr) * LDK + sc]); sr_[i].vs1 = *reinterpret_cast<const bf16x8*>(&Vh[(long)((k0) + 32 + sr) * LDK + sc]); \
;     sr_[i].ks0 = *reinterpret_cast<const bf16x8*>(&Kh[(long)((k0) + sr) * LDK + sc]); sr_[i].ks1 = *reinterpret_cast<const bf16x8*>(&Kh[(long)((k0) + 32 + sr) * LDK + sc]); } while (0)
; #define SWRITE(b, i) do { *(bf16x8*)((char*)V_lds + (b) * SHM_V + vst0) = sr_[i].vs0;          \
;     *(bf16x8*)((char*)V_lds + (b) * SHM_V + vst1) = sr_[i].vs1; int kc = sc * 2;               \
;     *(bf16x8*)((char*)K_lds + (b) * SHM_K + KSWZ(sr, kc)) = sr_[i].ks0;                       \
;     *(bf16x8*)((char*)K_lds + (b) * SHM_K + KSWZ(32 + sr, kc)) = sr_[i].ks1; } while (0)
; #define SWAIT() asm volatile("s_waitcnt vmcnt(4)" ::: "memory")
; __device__ __forceinline__ void qkt(f32x16& p0, f32x16& p1, const bf16* Ks, const bf16x8* qr, int r32, int hi) {
;   p0 = f32x16{}; p1 = f32x16{};
; #pragma unroll
;   for (int d0 = 0; d0 < 8; ++d0) { int cb = (d0 * 16 + hi * 8) * 2;
;     bf16x8 b0 = *reinterpret_cast<const bf16x8*>((const char*)Ks + KSWZ(r32, cb));
;     bf16x8 b1 = *reinterpret_cast<const bf16x8*>((const char*)Ks + KSWZ(32 + r32, cb));
;     p0 = __builtin_amdgcn_mfma_f32_32x32x16_bf16(b0, qr[d0], p0, 0, 0, 0);
;     p1 = __builtin_amdgcn_mfma_f32_32x32x16_bf16(b1, qr[d0], p1, 0, 0, 0); }
; __device__ __forceinline__ void attn_unit_fast(const bf16* __restrict__ Qb, const bf16* __restrict__ Kh, const bf16* __restrict__ Vh, bf16* __restrict__ Ob, int NT, char* lds, int t0, const float* __restrict__ qg) {
;     ...
;   qkt(pA0, pA1, K_lds, qr, r32, hi); partialSM_fast(pA0, pA1);
;   SLOAD(SO, KVBLK); SLOAD(SE, 2 * KVBLK);
;   SWAIT(); SWRITE(1, SO); __syncthreads();
	s_add_u32 s0, s48, s0
	s_addc_u32 s1, s49, s1
	v_readfirstlane_b32 s5, v195
	v_lshrrev_b32_e32 v245, 4, v195
	v_xor_b32_e32 v244, v245, v195
	v_and_b32_e32 v244, 15, v244
	v_lshlrev_b32_e32 v244, 4, v244
	v_lshl_or_b32 v244, v245, 8, v244
	v_add_u32_e32 v244, 0x6404000, v244
	v_add_u32_e32 v245, 0x2000, v244
	v_bfe_u32 v254, v195, 2, 2
	v_bfe_u32 v253, v195, 7, 1
	v_lshl_or_b32 v254, v253, 2, v254
	v_bfe_u32 v253, v195, 4, 1
	v_lshl_or_b32 v254, v253, 3, v254
	v_bfe_u32 v253, v195, 8, 1
	v_lshl_or_b32 v254, v253, 4, v254
	v_bfe_u32 v253, v195, 5, 2
	v_lshlrev_b32_e32 v253, 6, v253
	v_lshl_or_b32 v253, v254, 8, v253
	v_and_b32_e32 v254, 3, v195
	v_lshl_or_b32 v253, v254, 4, v253
	v_add_u32_e32 v253, 0x7100000, v253
	v_add_u32_e32 v254, 0x2000, v253
	s_lshl_b32 s5, s5, 4
	s_add_u32 m0, s5, 0x14800
	s_nop 0
	global_load_lds_dwordx4 v244, s[0:1]
	s_add_u32 m0, s5, 0x16800
	s_nop 0
	global_load_lds_dwordx4 v245, s[0:1]
	s_add_u32 s0, s0, 0x4000
	s_addc_u32 s1, s1, 0
	s_add_u32 m0, s5, 0x18800
	s_nop 0
	global_load_lds_dwordx4 v244, s[0:1]
	s_add_u32 m0, s5, 0x1a800
	s_nop 0
	global_load_lds_dwordx4 v245, s[0:1]
	s_add_u32 m0, s5, 0x4000
	s_nop 0
	global_load_lds_dwordx4 v253, s[0:1]
	s_add_u32 m0, s5, 0x6000
	s_nop 0
	global_load_lds_dwordx4 v254, s[0:1]
	s_add_u32 s0, s0, 0x4000
	s_addc_u32 s1, s1, 0
	s_add_u32 m0, s5, 0x1c800
	s_nop 0
	global_load_lds_dwordx4 v244, s[0:1]
	s_add_u32 m0, s5, 0x1e800
	s_nop 0
	global_load_lds_dwordx4 v245, s[0:1]
	s_add_u32 m0, s5, 0x8000
	s_nop 0
	global_load_lds_dwordx4 v253, s[0:1]
	s_add_u32 m0, s5, 0xa000
	s_nop 0
	global_load_lds_dwordx4 v254, s[0:1]
	s_add_u32 s0, s0, 0x4000
	s_addc_u32 s1, s1, 0
	ds_read_b128 v[0:3], v194
	ds_read_b128 v[28:31], v194 offset:8192
	v_cvt_pk_bf16_f32 v133, v6, v5
	v_pk_mul_f32 v[4:5], v[62:63], v[182:183] op_sel_hi:[0,1]
	v_pk_mul_f32 v[20:21], v[4:5], v[20:21]
	s_waitcnt lgkmcnt(0)
	v_mfma_f32_32x32x16_bf16 v[64:79], v[28:31], v[112:115], 0
	v_mul_f32_e64 v38, v21, v140
	v_mul_f32_e64 v39, v20, v140
	v_fma_f32 v40, v20, v136, -v38
	v_fma_f32 v41, v21, v137, -v39
	v_fma_f32 v20, v20, v136, v38
	v_fma_f32 v21, v21, v136, v39
	v_mov_b32_e32 v197, 0
	v_or_b32_e32 v20, 32, v176
	v_bitop3_b32 v20, v20, v42, v43 bitop3:0xde
	v_cvt_pk_bf16_f32 v134, v40, v21
	v_add_u32_e32 v196, 0x10800, v20
	v_pk_mul_f32 v[20:21], v[62:63], v[80:81] op_sel_hi:[0,1]
	v_pk_mul_f32 v[20:21], v[20:21], v[22:23]
	ds_read_b128 v[38:41], v196
	v_pk_mul_f32 v[22:23], v[20:21], v[60:61] op_sel:[1,0] op_sel_hi:[0,0]
	v_pk_fma_f32 v[28:29], v[20:21], v[204:205], v[22:23] neg_lo:[0,0,1] neg_hi:[0,0,1]
	v_pk_fma_f32 v[20:21], v[20:21], v[204:205], v[22:23] op_sel_hi:[1,0,1]
	v_mfma_f32_32x32x16_bf16 v[0:15], v[0:3], v[112:115], 0
	v_cvt_pk_bf16_f32 v135, v28, v21
	ds_read_b128 v[20:23], v196 offset:8192
	v_mul_f32_e64 v28, v62, v154
	v_mul_f32_e64 v29, v62, v155
	v_mul_f32_e64 v24, v28, v24
	v_mul_f32_e64 v25, v29, v25
	v_or_b32_e32 v28, 64, v176
	v_bitop3_b32 v28, v28, v42, v43 bitop3:0xde
	v_add_u32_e32 v198, 0x10800, v28
	ds_read_b128 v[28:31], v198
	s_waitcnt lgkmcnt(2)
	v_mfma_f32_32x32x16_bf16 v[0:15], v[38:41], v[116:119], v[0:15]
	v_mul_f32_e64 v38, v25, v208
	v_mul_f32_e64 v39, v24, v208
	v_mov_b32_e32 v40, v197
	v_mov_b32_e32 v41, v197
	v_mov_b32_e32 v44, v197
	v_mov_b32_e32 v45, v197
	v_mov_b32_e32 v46, v197
	v_mov_b32_e32 v47, v197
	s_waitcnt lgkmcnt(1)
	v_mfma_f32_32x32x16_bf16 v[64:79], v[20:23], v[116:119], v[64:79]
	v_fma_f32 v20, v24, v206, -v38
	v_fma_f32 v21, v25, v207, -v39
	v_fma_f32 v22, v24, v206, v38
	v_fma_f32 v23, v25, v206, v39
	v_mov_b32_e32 v52, v197
	v_cvt_pk_bf16_f32 v136, v20, v23
	v_pk_mul_f32 v[20:21], v[62:63], v[82:83] op_sel_hi:[0,1]
	v_pk_mul_f32 v[24:25], v[20:21], v[26:27]
	ds_read_b128 v[20:23], v198 offset:8192
	v_pk_mul_f32 v[26:27], v[24:25], v[210:211] op_sel:[1,0] op_sel_hi:[0,0]
	s_waitcnt lgkmcnt(1)
	v_mfma_f32_32x32x16_bf16 v[0:15], v[28:31], v[120:123], v[0:15]
	v_fma_f32 v28, v24, v216, -v26
	v_fma_f32 v29, v25, v217, -v27
	v_fma_f32 v24, v24, v216, v26
	v_fma_f32 v25, v25, v216, v27
	v_lshl_add_u64 v[30:31], v[36:37], 0, s[30:31]
	v_or_b32_e32 v24, 0x60, v176
	v_bitop3_b32 v24, v24, v42, v43 bitop3:0xde
	v_add_u32_e32 v199, 0x10800, v24
	v_cvt_pk_bf16_f32 v137, v28, v25
	ds_read_b128 v[24:27], v199
	s_waitcnt lgkmcnt(1)
	v_mfma_f32_32x32x16_bf16 v[64:79], v[20:23], v[120:123], v[64:79]
	v_mul_f32_e64 v20, v62, v152
	v_mul_f32_e64 v21, v62, v153
	v_mul_f32_e64 v16, v20, v16
	v_mul_f32_e64 v17, v21, v17
	v_lshl_add_u64 v[38:39], s[66:67], 0, v[30:31]
	v_pk_mul_f32 v[20:21], v[16:17], v[230:231] op_sel:[1,0] op_sel_hi:[0,0]
	v_pk_fma_f32 v[22:23], v[16:17], v[228:229], v[20:21] neg_lo:[0,0,1] neg_hi:[0,0,1]
	v_pk_fma_f32 v[16:17], v[16:17], v[228:229], v[20:21] op_sel_hi:[1,0,1]
	v_mov_b32_e32 v53, v197
	v_cvt_pk_bf16_f32 v138, v22, v17
	ds_read_b128 v[20:23], v199 offset:8192
	v_or_b32_e32 v16, 0x80, v176
	v_bitop3_b32 v16, v16, v42, v43 bitop3:0xde
	v_add_u32_e32 v200, 0x10800, v16
	v_lshl_add_u64 v[16:17], v[36:37], 0, s[24:25]
	s_waitcnt lgkmcnt(1)
	v_mfma_f32_32x32x16_bf16 v[0:15], v[24:27], v[124:127], v[0:15]
	ds_read_b128 v[24:27], v200
	v_lshl_add_u64 v[28:29], s[66:67], 0, v[16:17]
	v_lshl_add_u64 v[16:17], s[44:45], 0, v[16:17]
	v_lshl_add_u64 v[28:29], s[44:45], 0, v[30:31]
	v_pk_mul_f32 v[16:17], v[62:63], v[84:85] op_sel_hi:[0,1]
	v_pk_mul_f32 v[16:17], v[16:17], v[18:19]
	s_waitcnt lgkmcnt(1)
	v_mfma_f32_32x32x16_bf16 v[64:79], v[20:23], v[124:127], v[64:79]
	v_mul_f32_e64 v18, v17, v212
	v_mul_f32_e64 v19, v16, v212
	v_fma_f32 v20, v16, v164, -v18
	v_fma_f32 v21, v17, v165, -v19
	v_fma_f32 v16, v16, v164, v18
	v_fma_f32 v17, v17, v164, v19
	v_mov_b32_e32 v28, v197
	v_cvt_pk_bf16_f32 v139, v20, v17
	ds_read_b128 v[16:19], v200 offset:8192
	v_pk_mul_f32 v[20:21], v[62:63], v[100:101] op_sel_hi:[0,1]
	s_waitcnt lgkmcnt(1)
; __device__ __forceinline__ void qkt(f32x16& p0, f32x16& p1, const bf16* Ks, const bf16x8* qr, int r32, int hi) {
;   p0 = f32x16{}; p1 = f32x16{};
; #pragma unroll
;   for (int d0 = 0; d0 < 8; ++d0) { int cb = (d0 * 16 + hi * 8) * 2;
;     bf16x8 b0 = *reinterpret_cast<const bf16x8*>((const char*)Ks + KSWZ(r32, cb));
;     bf16x8 b1 = *reinterpret_cast<const bf16x8*>((const char*)Ks + KSWZ(32 + r32, cb));
;     p0 = __builtin_amdgcn_mfma_f32_32x32x16_bf16(b0, qr[d0], p0, 0, 0, 0);
;     p1 = __builtin_amdgcn_mfma_f32_32x32x16_bf16(b1, qr[d0], p1, 0, 0, 0); }
; __device__ __forceinline__ void partialSM_fast(f32x16& p0, f32x16& p1) {
; #pragma unroll
;   for (int r = 0; r < 16; ++r) p0[r] = __builtin_amdgcn_exp2f(p0[r]);
; }
; __device__ __forceinline__ void finishSM_fast(f32x16& p0, f32x16& p1, float& l_reg, bf16x8& pa0, bf16x8& pa1, bf16x8& pa2, bf16x8& pa3) {
; #pragma unroll
;   for (int r = 0; r < 16; ++r) p1[r] = __builtin_amdgcn_exp2f(p1[r]);
;   float ps = 0;
; #pragma unroll
;   for (int r = 0; r < 16; ++r) ps += p0[r];
; #pragma unroll
;   for (int r = 0; r < 16; ++r) ps += p1[r];
;   { auto rr = __builtin_amdgcn_permlane32_swap(__float_as_uint(ps), __float_as_uint(ps), false, false);
;     ps = __uint_as_float(rr[0]) + __uint_as_float(rr[1]); }
;   l_reg += ps;
;     ...
;   PK4(p0, 0, pa0); PK4(p0, 8, pa1); PK4(p1, 0, pa2); PK4(p1, 8, pa3);
;     ...
; }
	v_mfma_f32_32x32x16_bf16 v[0:15], v[24:27], v[128:131], v[0:15]
	v_mul_f32_e64 v24, v20, v56
	v_mul_f32_e64 v25, v21, v57
	v_or_b32_e32 v20, 0xa0, v176
	v_bitop3_b32 v20, v20, v42, v43 bitop3:0xde
	v_add_u32_e32 v201, 0x10800, v20
	ds_read_b128 v[20:23], v201
	v_pk_mul_f32 v[26:27], v[24:25], v[214:215] op_sel:[1,0] op_sel_hi:[0,0]
	v_mov_b32_e32 v29, v197
	s_waitcnt lgkmcnt(1)
	v_mfma_f32_32x32x16_bf16 v[64:79], v[16:19], v[128:131], v[64:79]
	v_fma_f32 v16, v24, v160, -v26
	v_fma_f32 v17, v25, v161, -v27
	v_fma_f32 v18, v24, v160, v26
	v_fma_f32 v19, v25, v160, v27
	v_mov_b32_e32 v30, v197
	v_cvt_pk_bf16_f32 v148, v16, v19
	v_pk_mul_f32 v[16:17], v[62:63], v[86:87] op_sel_hi:[0,1]
	v_pk_mul_f32 v[24:25], v[16:17], v[58:59]
	ds_read_b128 v[16:19], v201 offset:8192
	v_pk_mul_f32 v[26:27], v[24:25], v[222:223] op_sel:[1,0] op_sel_hi:[0,0]
	s_waitcnt lgkmcnt(1)
	v_mfma_f32_32x32x16_bf16 v[0:15], v[20:23], v[132:135], v[0:15]
	v_fma_f32 v20, v24, v224, -v26
	v_fma_f32 v21, v25, v225, -v27
	v_fma_f32 v22, v24, v224, v26
	v_fma_f32 v23, v25, v224, v27
	v_mov_b32_e32 v31, v197
	v_cvt_pk_bf16_f32 v149, v20, v23
	v_or_b32_e32 v20, 0xc0, v176
	v_bitop3_b32 v20, v20, v42, v43 bitop3:0xde
	v_add_u32_e32 v202, 0x10800, v20
	ds_read_b128 v[20:23], v202
	s_waitcnt lgkmcnt(1)
	v_mfma_f32_32x32x16_bf16 v[64:79], v[16:19], v[132:135], v[64:79]
	v_mul_f32_e64 v16, v62, v90
	v_mul_f32_e64 v17, v62, v91
	v_mul_f32_e64 v16, v16, v48
	v_mul_f32_e64 v17, v17, v49
	v_mov_b32_e32 v38, v197
	v_pk_mul_f32 v[18:19], v[16:17], v[220:221] op_sel:[1,0] op_sel_hi:[0,0]
	v_pk_fma_f32 v[24:25], v[16:17], v[226:227], v[18:19] neg_lo:[0,0,1] neg_hi:[0,0,1]
	v_pk_fma_f32 v[16:17], v[16:17], v[226:227], v[18:19] op_sel_hi:[1,0,1]
	v_mov_b32_e32 v39, v197
	v_cvt_pk_bf16_f32 v150, v24, v17
	ds_read_b128 v[16:19], v202 offset:8192
	s_waitcnt lgkmcnt(1)
	v_mfma_f32_32x32x16_bf16 v[0:15], v[20:23], v[136:139], v[0:15]
	v_mul_f32_e64 v20, v62, v88
	v_mul_f32_e64 v21, v62, v89
	v_mul_f32_e64 v24, v20, v50
	v_mul_f32_e64 v25, v21, v51
	v_or_b32_e32 v20, 0xe0, v176
	v_bitop3_b32 v20, v20, v42, v43 bitop3:0xde
	v_pk_mul_f32 v[26:27], v[24:25], v[218:219] op_sel:[1,0] op_sel_hi:[0,0]
	v_add_u32_e32 v203, 0x10800, v20
	ds_read_b128 v[20:23], v203
	s_waitcnt lgkmcnt(1)
	v_mfma_f32_32x32x16_bf16 v[64:79], v[16:19], v[136:139], v[64:79]
	v_fma_f32 v16, v24, v32, -v26
	v_fma_f32 v17, v25, v33, -v27
	v_fma_f32 v18, v24, v32, v26
	v_fma_f32 v19, v25, v32, v27
	v_lshlrev_b32_e32 v24, 3, v179
	v_cvt_pk_bf16_f32 v151, v16, v19
	v_and_b32_e32 v16, 0xc0, v33
	v_and_or_b32 v25, v24, 24, v16
	ds_read_b128 v[16:19], v203 offset:8192
	s_waitcnt lgkmcnt(1)
	v_mfma_f32_32x32x16_bf16 v[0:15], v[20:23], v[148:151], v[0:15]
	v_lshlrev_b32_e32 v20, 1, v195
	v_and_b32_e32 v20, 32, v20
	v_and_b32_e32 v21, 0x100, v24
	v_or3_b32 v24, v25, v20, v21
	v_lshl_add_u64 v[20:21], v[36:37], 0, s[38:39]
	v_lshl_add_u64 v[22:23], s[66:67], 0, v[20:21]
	v_add_u32_e32 v188, s4, v24
	s_waitcnt lgkmcnt(0)
	v_mfma_f32_32x32x16_bf16 v[64:79], v[16:19], v[148:151], v[64:79]
	v_lshl_add_u64 v[16:17], v[36:37], 0, s[34:35]
	v_lshl_add_u64 v[18:19], s[66:67], 0, v[16:17]
	v_lshl_add_u64 v[16:17], s[44:45], 0, v[16:17]
	v_lshl_add_u64 v[18:19], s[44:45], 0, v[20:21]
	s_nop 7
	s_nop 7
	v_and_b32_e32 v204, 15, v191
	v_xor_b32_e32 v204, v204, v193
	v_lshlrev_b32_e32 v204, 4, v204
	v_lshlrev_b32_e32 v205, 8, v191
	v_add_u32_e32 v205, 0x10800, v205
	v_xor_b32_e32 v194, 0x0, v204
	v_add_u32_e32 v194, v194, v205
	v_xor_b32_e32 v196, 0x20, v204
	v_add_u32_e32 v196, v196, v205
	v_xor_b32_e32 v198, 0x40, v204
	v_add_u32_e32 v198, v198, v205
	v_xor_b32_e32 v199, 0x60, v204
	v_add_u32_e32 v199, v199, v205
	v_xor_b32_e32 v200, 0x80, v204
	v_add_u32_e32 v200, v200, v205
	v_xor_b32_e32 v201, 0xa0, v204
	v_add_u32_e32 v201, v201, v205
	v_xor_b32_e32 v202, 0xc0, v204
	v_add_u32_e32 v202, v202, v205
	v_xor_b32_e32 v203, 0xe0, v204
	v_add_u32_e32 v203, v203, v205
	v_exp_f32_e32 v96, v0
	v_exp_f32_e32 v97, v1
	v_exp_f32_e32 v98, v2
	v_exp_f32_e32 v99, v3
	v_exp_f32_e32 v100, v4
	v_exp_f32_e32 v101, v5
	v_exp_f32_e32 v102, v6
	v_exp_f32_e32 v103, v7
	v_exp_f32_e32 v104, v8
	v_exp_f32_e32 v105, v9
	v_exp_f32_e32 v106, v10
	v_exp_f32_e32 v107, v11
	v_exp_f32_e32 v108, v12
	v_exp_f32_e32 v109, v13
	v_exp_f32_e32 v110, v14
	v_exp_f32_e32 v111, v15
	v_exp_f32_e32 v64, v64
	v_exp_f32_e32 v65, v65
	v_exp_f32_e32 v66, v66
	v_exp_f32_e32 v67, v67
	v_exp_f32_e32 v68, v68
	v_exp_f32_e32 v69, v69
	v_exp_f32_e32 v70, v70
	v_exp_f32_e32 v71, v71
	v_exp_f32_e32 v72, v72
	v_exp_f32_e32 v73, v73
	v_exp_f32_e32 v74, v74
	v_exp_f32_e32 v75, v75
	v_exp_f32_e32 v76, v76
	v_exp_f32_e32 v77, v77
	v_exp_f32_e32 v78, v78
	v_exp_f32_e32 v79, v79
	v_cvt_pk_bf16_f32 v140, v96, v97
	v_cvt_pk_bf16_f32 v142, v100, v101
	v_cvt_pk_bf16_f32 v141, v98, v99
	v_cvt_pk_bf16_f32 v143, v102, v103
	s_nop 1
	v_permlane32_swap_b32_e32 v140, v142
	s_nop 1
	v_permlane32_swap_b32_e32 v141, v143
	v_cvt_pk_bf16_f32 v144, v104, v105
	v_cvt_pk_bf16_f32 v146, v108, v109
	v_cvt_pk_bf16_f32 v145, v106, v107
	v_cvt_pk_bf16_f32 v147, v110, v111
	s_nop 1
	v_permlane32_swap_b32_e32 v144, v146
	s_nop 1
	v_permlane32_swap_b32_e32 v145, v147
	v_mov_b32_e32 v197, 0
	v_add_f32_e32 v238, v96, v97
	v_add_f32_e32 v238, v98, v238
	v_add_f32_e32 v238, v99, v238
	v_add_f32_e32 v238, v100, v238
	v_add_f32_e32 v238, v101, v238
	v_add_f32_e32 v238, v102, v238
	v_add_f32_e32 v238, v103, v238
	v_add_f32_e32 v238, v104, v238
	v_add_f32_e32 v238, v105, v238
	v_add_f32_e32 v238, v106, v238
	v_add_f32_e32 v238, v107, v238
	v_add_f32_e32 v238, v108, v238
	v_add_f32_e32 v238, v109, v238
	v_add_f32_e32 v238, v110, v238
; #define SBAR() __builtin_amdgcn_sched_barrier(0)
; #define SLOAD(i, k0) do { sr_[i].vs0 = *reinterpret_cast<const bf16x8*>(&Vh[(long)((k0) + sr) * LDK + sc]); sr_[i].vs1 = *reinterpret_cast<const bf16x8*>(&Vh[(long)((k0) + 32 + sr) * LDK + sc]); \
;     sr_[i].ks0 = *reinterpret_cast<const bf16x8*>(&Kh[(long)((k0) + sr) * LDK + sc]); sr_[i].ks1 = *reinterpret_cast<const bf16x8*>(&Kh[(long)((k0) + 32 + sr) * LDK + sc]); } while (0)
; #define SWRITE(b, i) do { *(bf16x8*)((char*)V_lds + (b) * SHM_V + vst0) = sr_[i].vs0;          \
;     *(bf16x8*)((char*)V_lds + (b) * SHM_V + vst1) = sr_[i].vs1; int kc = sc * 2;               \
;     *(bf16x8*)((char*)K_lds + (b) * SHM_K + KSWZ(sr, kc)) = sr_[i].ks0;                       \
;     *(bf16x8*)((char*)K_lds + (b) * SHM_K + KSWZ(32 + sr, kc)) = sr_[i].ks1; } while (0)
; #define SWAIT() asm volatile("s_waitcnt vmcnt(4)" ::: "memory")
; __device__ __forceinline__ void finishSM_fast(f32x16& p0, f32x16& p1, float& l_reg, bf16x8& pa0, bf16x8& pa1, bf16x8& pa2, bf16x8& pa3) {
; #pragma unroll
;   for (int r = 0; r < 16; ++r) p1[r] = __builtin_amdgcn_exp2f(p1[r]);
;   float ps = 0;
; #pragma unroll
;   for (int r = 0; r < 16; ++r) ps += p0[r];
; #pragma unroll
;   for (int r = 0; r < 16; ++r) ps += p1[r];
;   { auto rr = __builtin_amdgcn_permlane32_swap(__float_as_uint(ps), __float_as_uint(ps), false, false);
;     ps = __uint_as_float(rr[0]) + __uint_as_float(rr[1]); }
;   l_reg += ps;
;     ...
;   PK4(p0, 0, pa0); PK4(p0, 8, pa1); PK4(p1, 0, pa2); PK4(p1, 8, pa3);
;     ...
; }
; __device__ __forceinline__ void attn_unit_fast(const bf16* __restrict__ Qb, const bf16* __restrict__ Kh, const bf16* __restrict__ Vh, bf16* __restrict__ Ob, int NT, char* lds, int t0, const float* __restrict__ qg) {
;     ...
;   for (int j = 1; j + 1 < NT; j += 2) {
;     SBAR(); qkt(pB0, pB1, (bf16*)((char*)K_lds + SHM_K), qr, r32, hi);
;     finishSM_fast(pA0, pA1, l_reg, pa0, pa1, pa2, pa3); SBAR();
;     if (j + 2 < NT) SLOAD(SO, (j + 2) * KVBLK); SBAR();
;     pv_d0(o, vb0, pa0, pa1, pa2, pa3); partialSM_fast(pB0, pB1);
;     __syncthreads(); SWAIT(); SWRITE(0, SE);
	v_add_f32_e32 v238, v111, v238
	v_add_f32_e32 v197, v238, v197
	v_mov_b32_e32 v0, 0
	v_mov_b32_e32 v1, 0
	v_mov_b32_e32 v2, 0
	v_mov_b32_e32 v3, 0
	v_mov_b32_e32 v4, 0
	v_mov_b32_e32 v5, 0
	v_mov_b32_e32 v6, 0
	v_mov_b32_e32 v7, 0
	v_mov_b32_e32 v8, 0
	v_mov_b32_e32 v9, 0
	v_mov_b32_e32 v10, 0
	v_mov_b32_e32 v11, 0
	v_mov_b32_e32 v12, 0
	v_mov_b32_e32 v13, 0
	v_mov_b32_e32 v14, 0
	v_mov_b32_e32 v15, 0
	v_mov_b32_e32 v16, 0
	v_mov_b32_e32 v17, 0
	v_mov_b32_e32 v18, 0
	v_mov_b32_e32 v19, 0
	v_mov_b32_e32 v20, 0
	v_mov_b32_e32 v21, 0
	v_mov_b32_e32 v22, 0
	v_mov_b32_e32 v23, 0
	v_mov_b32_e32 v24, 0
	v_mov_b32_e32 v25, 0
	v_mov_b32_e32 v26, 0
	v_mov_b32_e32 v27, 0
	v_mov_b32_e32 v28, 0
	v_mov_b32_e32 v29, 0
	v_mov_b32_e32 v30, 0
	v_mov_b32_e32 v31, 0
	v_mov_b32_e32 v32, 0
	v_mov_b32_e32 v33, 0
	v_mov_b32_e32 v34, 0
	v_mov_b32_e32 v35, 0
	v_mov_b32_e32 v36, 0
	v_mov_b32_e32 v37, 0
	v_mov_b32_e32 v38, 0
	v_mov_b32_e32 v39, 0
	v_mov_b32_e32 v40, 0
	v_mov_b32_e32 v41, 0
	v_mov_b32_e32 v42, 0
	v_mov_b32_e32 v43, 0
	v_mov_b32_e32 v44, 0
	v_mov_b32_e32 v45, 0
	v_mov_b32_e32 v46, 0
	v_mov_b32_e32 v47, 0
	v_mov_b32_e32 v48, 0
	v_mov_b32_e32 v49, 0
	v_mov_b32_e32 v50, 0
	v_mov_b32_e32 v51, 0
	v_mov_b32_e32 v52, 0
	v_mov_b32_e32 v53, 0
	v_mov_b32_e32 v54, 0
	v_mov_b32_e32 v55, 0
	v_mov_b32_e32 v56, 0
	v_mov_b32_e32 v57, 0
	v_mov_b32_e32 v58, 0
	v_mov_b32_e32 v59, 0
	v_mov_b32_e32 v60, 0
	v_mov_b32_e32 v61, 0
	v_mov_b32_e32 v62, 0
	v_mov_b32_e32 v63, 0
	s_lshr_b32 s4, s94, 2
	s_cmp_ge_u32 s5, 0x1000
	s_cbranch_scc0 .Lattn_noprio
	s_setprio 1
.Lattn_noprio:
	s_waitcnt vmcnt(4)
	s_barrier
	ds_read_b128 v[206:209], v194 offset:16384
	ds_read_b128 v[210:213], v196 offset:16384
	ds_read_b128 v[214:217], v198 offset:16384
	ds_read_b128 v[218:221], v199 offset:16384
.Lattn_loop:
	s_waitcnt lgkmcnt(3)
	v_mfma_f32_32x32x16_bf16 v[160:175], v[206:209], v[112:115], 0
	ds_read_b128 v[206:209], v200 offset:16384
	v_cvt_pk_bf16_f32 v152, v64, v65
	v_cvt_pk_bf16_f32 v154, v68, v69
	v_add_f32_e32 v239, v64, v65
	v_add_f32_e32 v239, v66, v239
	s_waitcnt lgkmcnt(3)
	v_mfma_f32_32x32x16_bf16 v[160:175], v[210:213], v[116:119], v[160:175]
	ds_read_b128 v[210:213], v201 offset:16384
	v_cvt_pk_bf16_f32 v153, v66, v67
	v_cvt_pk_bf16_f32 v155, v70, v71
	v_add_f32_e32 v239, v67, v239
	v_add_f32_e32 v239, v68, v239
	s_waitcnt lgkmcnt(3)
	v_mfma_f32_32x32x16_bf16 v[160:175], v[214:217], v[120:123], v[160:175]
	ds_read_b128 v[214:217], v202 offset:16384
	v_permlane32_swap_b32_e32 v152, v154
	v_add_f32_e32 v239, v69, v239
	v_add_f32_e32 v239, v70, v239
	s_waitcnt lgkmcnt(3)
	v_mfma_f32_32x32x16_bf16 v[160:175], v[218:221], v[124:127], v[160:175]
	ds_read_b128 v[218:221], v203 offset:16384
	v_permlane32_swap_b32_e32 v153, v155
	v_add_f32_e32 v239, v71, v239
	v_add_f32_e32 v239, v72, v239
	s_waitcnt lgkmcnt(3)
	v_mfma_f32_32x32x16_bf16 v[160:175], v[206:209], v[128:131], v[160:175]
	ds_read_b128 v[206:209], v194 offset:24576
	v_cvt_pk_bf16_f32 v156, v72, v73
	v_cvt_pk_bf16_f32 v158, v76, v77
	v_add_f32_e32 v239, v73, v239
	v_add_f32_e32 v239, v74, v239
	s_barrier
	s_waitcnt lgkmcnt(3)
	v_mfma_f32_32x32x16_bf16 v[160:175], v[210:213], v[132:135], v[160:175]
	ds_read_b128 v[210:213], v196 offset:24576
	v_cvt_pk_bf16_f32 v157, v74, v75
	v_cvt_pk_bf16_f32 v159, v78, v79
	v_add_f32_e32 v239, v75, v239
	v_add_f32_e32 v239, v76, v239
	s_waitcnt lgkmcnt(3)
	v_mfma_f32_32x32x16_bf16 v[160:175], v[214:217], v[136:139], v[160:175]
	ds_read_b128 v[214:217], v198 offset:24576
	v_permlane32_swap_b32_e32 v156, v158
	v_add_f32_e32 v239, v77, v239
	v_add_f32_e32 v239, v78, v239
	s_waitcnt lgkmcnt(3)
	v_mfma_f32_32x32x16_bf16 v[160:175], v[218:221], v[148:151], v[160:175]
	ds_read_b128 v[218:221], v199 offset:24576
	v_permlane32_swap_b32_e32 v157, v159
	v_add_f32_e32 v239, v79, v239
	v_add_f32_e32 v197, v239, v197
	s_waitcnt lgkmcnt(3)
	v_mfma_f32_32x32x16_bf16 v[80:95], v[206:209], v[112:115], 0
	ds_read_b128 v[206:209], v200 offset:24576
	s_add_u32 m0, s5, 0x10800
	s_nop 0
	global_load_lds_dwordx4 v244, s[0:1]
	s_waitcnt lgkmcnt(3)
	v_mfma_f32_32x32x16_bf16 v[80:95], v[210:213], v[116:119], v[80:95]
	ds_read_b128 v[210:213], v201 offset:24576
	s_add_u32 m0, s5, 0x12800
	s_nop 0
	global_load_lds_dwordx4 v245, s[0:1]
	s_waitcnt lgkmcnt(3)
	v_mfma_f32_32x32x16_bf16 v[80:95], v[214:217], v[120:123], v[80:95]
	ds_read_b128 v[214:217], v202 offset:24576
	v_exp_f32_e32 v160, v160
	v_exp_f32_e32 v161, v161
	ds_read_b64_tr_b16 v[222:223], v188
	ds_read_b64_tr_b16 v[224:225], v188 offset:2048
	s_waitcnt lgkmcnt(5)
	v_mfma_f32_32x32x16_bf16 v[80:95], v[218:221], v[124:127], v[80:95]
	ds_read_b128 v[218:221], v203 offset:24576
	v_exp_f32_e32 v162, v162
	v_exp_f32_e32 v163, v163
	ds_read_b64_tr_b16 v[226:227], v188 offset:512
	ds_read_b64_tr_b16 v[228:229], v188 offset:2560
	s_waitcnt lgkmcnt(7)
	v_mfma_f32_32x32x16_bf16 v[80:95], v[206:209], v[128:131], v[80:95]
	v_exp_f32_e32 v164, v164
	v_exp_f32_e32 v165, v165
	ds_read_b64_tr_b16 v[230:231], v188 offset:1024
	ds_read_b64_tr_b16 v[232:233], v188 offset:3072
	s_waitcnt lgkmcnt(8)
	v_mfma_f32_32x32x16_bf16 v[80:95], v[210:213], v[132:135], v[80:95]
	v_exp_f32_e32 v166, v166
	v_exp_f32_e32 v167, v167
	ds_read_b64_tr_b16 v[234:235], v188 offset:1536
	ds_read_b64_tr_b16 v[236:237], v188 offset:3584
	s_waitcnt lgkmcnt(9)
	v_mfma_f32_32x32x16_bf16 v[80:95], v[214:217], v[136:139], v[80:95]
	v_exp_f32_e32 v168, v168
	v_exp_f32_e32 v169, v169
	ds_read_b64_tr_b16 v[240:241], v188 offset:4096
	ds_read_b64_tr_b16 v[242:243], v188 offset:6144
	s_waitcnt lgkmcnt(8)
; #define SBAR() __builtin_amdgcn_sched_barrier(0)
; #define SWAIT() asm volatile("s_waitcnt vmcnt(4)" ::: "memory")
; #define MASKLAST(P0, P1) do { _Pragma("unroll") for (int r = 8; r < 16; ++r) P0[r] = -1e30f; _Pragma("unroll") for (int r = 0; r < 16; ++r) P1[r] = -1e30f; } while (0)
; template <int D0> __device__ __forceinline__ void pv_one(f32x16& od, int vb, bf16x8 pa0, bf16x8 pa1, bf16x8 pa2, bf16x8 pa3) {
;   const s16x4 l0 = tr_read<v_rd_off(D0, 0, 0)>(vb), h0 = tr_read<v_rd_off(D0, 0, 1)>(vb), l1 = tr_read<v_rd_off(D0, 1, 0)>(vb), h1 = tr_read<v_rd_off(D0, 1, 1)>(vb);
;   const s16x4 l2 = tr_read<v_rd_off(D0, 2, 0)>(vb), h2 = tr_read<v_rd_off(D0, 2, 1)>(vb), l3 = tr_read<v_rd_off(D0, 3, 0)>(vb), h3 = tr_read<v_rd_off(D0, 3, 1)>(vb);
;   asm volatile("s_waitcnt lgkmcnt(0)" ::: "memory"); SBAR();
;     ...
;   od = __builtin_amdgcn_mfma_f32_32x32x16_bf16(pa0, PK(l0, h0), od, 0, 0, 0);
;   od = __builtin_amdgcn_mfma_f32_32x32x16_bf16(pa1, PK(l1, h1), od, 0, 0, 0);
;   od = __builtin_amdgcn_mfma_f32_32x32x16_bf16(pa2, PK(l2, h2), od, 0, 0, 0);
;   od = __builtin_amdgcn_mfma_f32_32x32x16_bf16(pa3, PK(l3, h3), od, 0, 0, 0);
;     ...
; }
; __device__ __forceinline__ void pv_d0(f32x16* o, int vb, bf16x8 pa0, bf16x8 pa1, bf16x8 pa2, bf16x8 pa3) {
;   pv_one<0>(o[0], vb, pa0, pa1, pa2, pa3); pv_one<1>(o[1], vb, pa0, pa1, pa2, pa3); pv_one<2>(o[2], vb, pa0, pa1, pa2, pa3); pv_one<3>(o[3], vb, pa0, pa1, pa2, pa3);
; }
; __device__ __forceinline__ void attn_unit_fast(const bf16* __restrict__ Qb, const bf16* __restrict__ Kh, const bf16* __restrict__ Vh, bf16* __restrict__ Ob, int NT, char* lds, int t0, const float* __restrict__ qg) {
;     ...
;   for (int j = 1; j + 1 < NT; j += 2) {
;     SBAR(); qkt(pB0, pB1, (bf16*)((char*)K_lds + SHM_K), qr, r32, hi);
;     finishSM_fast(pA0, pA1, l_reg, pa0, pa1, pa2, pa3); SBAR();
;     if (j + 2 < NT) SLOAD(SO, (j + 2) * KVBLK); SBAR();
;     pv_d0(o, vb0, pa0, pa1, pa2, pa3); partialSM_fast(pB0, pB1);
;     __syncthreads(); SWAIT(); SWRITE(0, SE);
;     __syncthreads();
;     SBAR(); qkt(pA0, pA1, K_lds, qr, r32, hi);
;     if (j + 2 == NT) MASKLAST(pA0, pA1);
;     finishSM_fast(pB0, pB1, l_reg, pa0, pa1, pa2, pa3); SBAR();
;     if (j + 3 < NT) SLOAD(SE, (j + 3) * KVBLK); SBAR();
;     pv_d0(o, vb0 + (int)SHM_V, pa0, pa1, pa2, pa3); partialSM_fast(pA0, pA1);
;     __syncthreads(); SWAIT(); SWRITE(1, SO);
;     __syncthreads();
;   }
	v_mfma_f32_32x32x16_bf16 v[80:95], v[218:221], v[148:151], v[80:95]
	v_exp_f32_e32 v170, v170
	v_exp_f32_e32 v171, v171
	ds_read_b64_tr_b16 v[180:181], v188 offset:4608
	ds_read_b64_tr_b16 v[182:183], v188 offset:6656
	v_mfma_f32_32x32x16_bf16 v[0:15], v[140:143], v[222:225], v[0:15]
	ds_read_b64_tr_b16 v[222:223], v188 offset:5120
	ds_read_b64_tr_b16 v[224:225], v188 offset:7168
	v_exp_f32_e32 v172, v172
	v_exp_f32_e32 v173, v173
	s_waitcnt lgkmcnt(10)
	v_mfma_f32_32x32x16_bf16 v[16:31], v[140:143], v[226:229], v[16:31]
	ds_read_b64_tr_b16 v[226:227], v188 offset:5632
	ds_read_b64_tr_b16 v[228:229], v188 offset:7680
	v_exp_f32_e32 v174, v174
	v_exp_f32_e32 v175, v175
	s_waitcnt lgkmcnt(10)
	v_mfma_f32_32x32x16_bf16 v[32:47], v[140:143], v[230:233], v[32:47]
	ds_read_b64_tr_b16 v[230:231], v188 offset:8192
	ds_read_b64_tr_b16 v[232:233], v188 offset:10240
	v_exp_f32_e32 v80, v80
	v_exp_f32_e32 v81, v81
	s_waitcnt lgkmcnt(10)
	v_mfma_f32_32x32x16_bf16 v[48:63], v[140:143], v[234:237], v[48:63]
	ds_read_b64_tr_b16 v[234:235], v188 offset:8704
	ds_read_b64_tr_b16 v[236:237], v188 offset:10752
	v_exp_f32_e32 v82, v82
	v_exp_f32_e32 v83, v83
	s_waitcnt lgkmcnt(10)
	v_mfma_f32_32x32x16_bf16 v[0:15], v[144:147], v[240:243], v[0:15]
	ds_read_b64_tr_b16 v[240:241], v188 offset:9216
	ds_read_b64_tr_b16 v[242:243], v188 offset:11264
	v_exp_f32_e32 v84, v84
	v_exp_f32_e32 v85, v85
	v_cvt_pk_bf16_f32 v140, v160, v161
	v_cvt_pk_bf16_f32 v142, v164, v165
	s_waitcnt lgkmcnt(10)
	v_mfma_f32_32x32x16_bf16 v[16:31], v[144:147], v[180:183], v[16:31]
	ds_read_b64_tr_b16 v[180:181], v188 offset:9728
	ds_read_b64_tr_b16 v[182:183], v188 offset:11776
	v_exp_f32_e32 v86, v86
	v_exp_f32_e32 v87, v87
	v_cvt_pk_bf16_f32 v141, v162, v163
	v_cvt_pk_bf16_f32 v143, v166, v167
	s_waitcnt lgkmcnt(10)
	v_mfma_f32_32x32x16_bf16 v[32:47], v[144:147], v[222:225], v[32:47]
	ds_read_b64_tr_b16 v[222:223], v188 offset:12288
	ds_read_b64_tr_b16 v[224:225], v188 offset:14336
	v_exp_f32_e32 v88, v88
	v_exp_f32_e32 v89, v89
	v_permlane32_swap_b32_e32 v140, v142
	s_waitcnt lgkmcnt(10)
	v_mfma_f32_32x32x16_bf16 v[48:63], v[144:147], v[226:229], v[48:63]
	ds_read_b64_tr_b16 v[226:227], v188 offset:12800
	ds_read_b64_tr_b16 v[228:229], v188 offset:14848
	v_exp_f32_e32 v90, v90
	v_exp_f32_e32 v91, v91
	v_permlane32_swap_b32_e32 v141, v143
	s_waitcnt lgkmcnt(10)
	v_mfma_f32_32x32x16_bf16 v[0:15], v[152:155], v[230:233], v[0:15]
	ds_read_b64_tr_b16 v[230:231], v188 offset:13312
	ds_read_b64_tr_b16 v[232:233], v188 offset:15360
	v_exp_f32_e32 v92, v92
	v_exp_f32_e32 v93, v93
	v_cvt_pk_bf16_f32 v144, v168, v169
	v_cvt_pk_bf16_f32 v146, v172, v173
	s_waitcnt lgkmcnt(10)
	v_mfma_f32_32x32x16_bf16 v[16:31], v[152:155], v[234:237], v[16:31]
	ds_read_b64_tr_b16 v[234:235], v188 offset:13824
	ds_read_b64_tr_b16 v[236:237], v188 offset:15872
	v_exp_f32_e32 v94, v94
	v_exp_f32_e32 v95, v95
	v_cvt_pk_bf16_f32 v145, v170, v171
	v_cvt_pk_bf16_f32 v147, v174, v175
	s_waitcnt vmcnt(6)
	s_barrier
	s_waitcnt lgkmcnt(10)
	v_mfma_f32_32x32x16_bf16 v[32:47], v[152:155], v[240:243], v[32:47]
	v_permlane32_swap_b32_e32 v144, v146
	s_add_u32 m0, s5, 0xc000
	v_add_f32_e32 v238, v160, v161
	global_load_lds_dwordx4 v253, s[0:1]
	v_add_f32_e32 v238, v162, v238
	v_add_f32_e32 v238, v163, v238
	s_waitcnt lgkmcnt(8)
	v_mfma_f32_32x32x16_bf16 v[48:63], v[152:155], v[180:183], v[48:63]
	v_permlane32_swap_b32_e32 v145, v147
	s_add_u32 m0, s5, 0xe000
	v_add_f32_e32 v238, v164, v238
	global_load_lds_dwordx4 v254, s[0:1]
	v_add_f32_e32 v238, v165, v238
	v_add_f32_e32 v238, v166, v238
	s_add_u32 s0, s0, 0x4000
	s_addc_u32 s1, s1, 0
	s_waitcnt lgkmcnt(6)
	v_mfma_f32_32x32x16_bf16 v[0:15], v[156:159], v[222:225], v[0:15]
	v_add_f32_e32 v238, v167, v238
	v_add_f32_e32 v238, v168, v238
	v_add_f32_e32 v238, v169, v238
	ds_read_b128 v[206:209], v194 offset:32768
	s_waitcnt lgkmcnt(5)
	v_mfma_f32_32x32x16_bf16 v[16:31], v[156:159], v[226:229], v[16:31]
	v_add_f32_e32 v238, v170, v238
	v_add_f32_e32 v238, v171, v238
	v_add_f32_e32 v238, v172, v238
	ds_read_b128 v[210:213], v196 offset:32768
	s_waitcnt lgkmcnt(4)
	v_mfma_f32_32x32x16_bf16 v[32:47], v[156:159], v[230:233], v[32:47]
	v_add_f32_e32 v238, v173, v238
	v_add_f32_e32 v238, v174, v238
	ds_read_b128 v[214:217], v198 offset:32768
	s_waitcnt lgkmcnt(3)
	v_mfma_f32_32x32x16_bf16 v[48:63], v[156:159], v[234:237], v[48:63]
	v_add_f32_e32 v238, v175, v238
	v_add_f32_e32 v197, v238, v197
	ds_read_b128 v[218:221], v199 offset:32768
	s_waitcnt lgkmcnt(3)
	v_mfma_f32_32x32x16_bf16 v[96:111], v[206:209], v[112:115], 0
	ds_read_b128 v[206:209], v200 offset:32768
	v_cvt_pk_bf16_f32 v152, v80, v81
	v_cvt_pk_bf16_f32 v154, v84, v85
	v_add_f32_e32 v239, v80, v81
	v_add_f32_e32 v239, v82, v239
	s_waitcnt lgkmcnt(3)
	v_mfma_f32_32x32x16_bf16 v[96:111], v[210:213], v[116:119], v[96:111]
	ds_read_b128 v[210:213], v201 offset:32768
	v_cvt_pk_bf16_f32 v153, v82, v83
	v_cvt_pk_bf16_f32 v155, v86, v87
	v_add_f32_e32 v239, v83, v239
	v_add_f32_e32 v239, v84, v239
	s_waitcnt lgkmcnt(3)
	v_mfma_f32_32x32x16_bf16 v[96:111], v[214:217], v[120:123], v[96:111]
	ds_read_b128 v[214:217], v202 offset:32768
	v_permlane32_swap_b32_e32 v152, v154
	v_add_f32_e32 v239, v85, v239
	v_add_f32_e32 v239, v86, v239
	s_waitcnt lgkmcnt(3)
	v_mfma_f32_32x32x16_bf16 v[96:111], v[218:221], v[124:127], v[96:111]
	ds_read_b128 v[218:221], v203 offset:32768
	v_permlane32_swap_b32_e32 v153, v155
	v_add_f32_e32 v239, v87, v239
	v_add_f32_e32 v239, v88, v239
	s_waitcnt lgkmcnt(3)
	v_mfma_f32_32x32x16_bf16 v[96:111], v[206:209], v[128:131], v[96:111]
	ds_read_b128 v[206:209], v194 offset:40960
	v_cvt_pk_bf16_f32 v156, v88, v89
	v_cvt_pk_bf16_f32 v158, v92, v93
	v_add_f32_e32 v239, v89, v239
	v_add_f32_e32 v239, v90, v239
	s_barrier
; #define SBAR() __builtin_amdgcn_sched_barrier(0)
; #define SWAIT() asm volatile("s_waitcnt vmcnt(4)" ::: "memory")
; #define MASKLAST(P0, P1) do { _Pragma("unroll") for (int r = 8; r < 16; ++r) P0[r] = -1e30f; _Pragma("unroll") for (int r = 0; r < 16; ++r) P1[r] = -1e30f; } while (0)
; template <int D0> __device__ __forceinline__ void pv_one(f32x16& od, int vb, bf16x8 pa0, bf16x8 pa1, bf16x8 pa2, bf16x8 pa3) {
;   const s16x4 l0 = tr_read<v_rd_off(D0, 0, 0)>(vb), h0 = tr_read<v_rd_off(D0, 0, 1)>(vb), l1 = tr_read<v_rd_off(D0, 1, 0)>(vb), h1 = tr_read<v_rd_off(D0, 1, 1)>(vb);
;   const s16x4 l2 = tr_read<v_rd_off(D0, 2, 0)>(vb), h2 = tr_read<v_rd_off(D0, 2, 1)>(vb), l3 = tr_read<v_rd_off(D0, 3, 0)>(vb), h3 = tr_read<v_rd_off(D0, 3, 1)>(vb);
;   asm volatile("s_waitcnt lgkmcnt(0)" ::: "memory"); SBAR();
;     ...
;   od = __builtin_amdgcn_mfma_f32_32x32x16_bf16(pa0, PK(l0, h0), od, 0, 0, 0);
;   od = __builtin_amdgcn_mfma_f32_32x32x16_bf16(pa1, PK(l1, h1), od, 0, 0, 0);
;   od = __builtin_amdgcn_mfma_f32_32x32x16_bf16(pa2, PK(l2, h2), od, 0, 0, 0);
;   od = __builtin_amdgcn_mfma_f32_32x32x16_bf16(pa3, PK(l3, h3), od, 0, 0, 0);
;     ...
; }
; __device__ __forceinline__ void pv_d0(f32x16* o, int vb, bf16x8 pa0, bf16x8 pa1, bf16x8 pa2, bf16x8 pa3) {
;   pv_one<0>(o[0], vb, pa0, pa1, pa2, pa3); pv_one<1>(o[1], vb, pa0, pa1, pa2, pa3); pv_one<2>(o[2], vb, pa0, pa1, pa2, pa3); pv_one<3>(o[3], vb, pa0, pa1, pa2, pa3);
; }
; __device__ __forceinline__ void attn_unit_fast(const bf16* __restrict__ Qb, const bf16* __restrict__ Kh, const bf16* __restrict__ Vh, bf16* __restrict__ Ob, int NT, char* lds, int t0, const float* __restrict__ qg) {
;     ...
;   for (int j = 1; j + 1 < NT; j += 2) {
;     SBAR(); qkt(pB0, pB1, (bf16*)((char*)K_lds + SHM_K), qr, r32, hi);
;     finishSM_fast(pA0, pA1, l_reg, pa0, pa1, pa2, pa3); SBAR();
;     if (j + 2 < NT) SLOAD(SO, (j + 2) * KVBLK); SBAR();
;     pv_d0(o, vb0, pa0, pa1, pa2, pa3); partialSM_fast(pB0, pB1);
;     __syncthreads(); SWAIT(); SWRITE(0, SE);
;     __syncthreads();
;     SBAR(); qkt(pA0, pA1, K_lds, qr, r32, hi);
;     if (j + 2 == NT) MASKLAST(pA0, pA1);
;     finishSM_fast(pB0, pB1, l_reg, pa0, pa1, pa2, pa3); SBAR();
;     if (j + 3 < NT) SLOAD(SE, (j + 3) * KVBLK); SBAR();
;     pv_d0(o, vb0 + (int)SHM_V, pa0, pa1, pa2, pa3); partialSM_fast(pA0, pA1);
;     __syncthreads(); SWAIT(); SWRITE(1, SO);
;     __syncthreads();
;   }
	s_waitcnt lgkmcnt(3)
	v_mfma_f32_32x32x16_bf16 v[96:111], v[210:213], v[132:135], v[96:111]
	ds_read_b128 v[210:213], v196 offset:40960
	v_cvt_pk_bf16_f32 v157, v90, v91
	v_cvt_pk_bf16_f32 v159, v94, v95
	v_add_f32_e32 v239, v91, v239
	v_add_f32_e32 v239, v92, v239
	s_waitcnt lgkmcnt(3)
	v_mfma_f32_32x32x16_bf16 v[96:111], v[214:217], v[136:139], v[96:111]
	ds_read_b128 v[214:217], v198 offset:40960
	v_permlane32_swap_b32_e32 v156, v158
	v_add_f32_e32 v239, v93, v239
	v_add_f32_e32 v239, v94, v239
	s_waitcnt lgkmcnt(3)
	v_mfma_f32_32x32x16_bf16 v[96:111], v[218:221], v[148:151], v[96:111]
	ds_read_b128 v[218:221], v199 offset:40960
	v_permlane32_swap_b32_e32 v157, v159
	v_add_f32_e32 v239, v95, v239
	v_add_f32_e32 v197, v239, v197
	s_waitcnt lgkmcnt(3)
	v_mfma_f32_32x32x16_bf16 v[64:79], v[206:209], v[112:115], 0
	ds_read_b128 v[206:209], v200 offset:40960
	s_add_u32 m0, s5, 0x14800
	s_nop 0
	global_load_lds_dwordx4 v244, s[0:1]
	s_waitcnt lgkmcnt(3)
	v_mfma_f32_32x32x16_bf16 v[64:79], v[210:213], v[116:119], v[64:79]
	ds_read_b128 v[210:213], v201 offset:40960
	s_add_u32 m0, s5, 0x16800
	s_nop 0
	global_load_lds_dwordx4 v245, s[0:1]
	s_waitcnt lgkmcnt(3)
	v_mfma_f32_32x32x16_bf16 v[64:79], v[214:217], v[120:123], v[64:79]
	ds_read_b128 v[214:217], v202 offset:40960
	v_exp_f32_e32 v96, v96
	v_exp_f32_e32 v97, v97
	ds_read_b64_tr_b16 v[222:223], v188 offset:16384
	ds_read_b64_tr_b16 v[224:225], v188 offset:18432
	s_waitcnt lgkmcnt(5)
	v_mfma_f32_32x32x16_bf16 v[64:79], v[218:221], v[124:127], v[64:79]
	ds_read_b128 v[218:221], v203 offset:40960
	v_exp_f32_e32 v98, v98
	v_exp_f32_e32 v99, v99
	ds_read_b64_tr_b16 v[226:227], v188 offset:16896
	ds_read_b64_tr_b16 v[228:229], v188 offset:18944
	s_waitcnt lgkmcnt(7)
	v_mfma_f32_32x32x16_bf16 v[64:79], v[206:209], v[128:131], v[64:79]
	v_exp_f32_e32 v100, v100
	v_exp_f32_e32 v101, v101
	ds_read_b64_tr_b16 v[230:231], v188 offset:17408
	ds_read_b64_tr_b16 v[232:233], v188 offset:19456
	s_waitcnt lgkmcnt(8)
	v_mfma_f32_32x32x16_bf16 v[64:79], v[210:213], v[132:135], v[64:79]
	v_exp_f32_e32 v102, v102
	v_exp_f32_e32 v103, v103
	ds_read_b64_tr_b16 v[234:235], v188 offset:17920
	ds_read_b64_tr_b16 v[236:237], v188 offset:19968
	s_waitcnt lgkmcnt(9)
	v_mfma_f32_32x32x16_bf16 v[64:79], v[214:217], v[136:139], v[64:79]
	v_exp_f32_e32 v104, v104
	v_exp_f32_e32 v105, v105
	ds_read_b64_tr_b16 v[240:241], v188 offset:20480
	ds_read_b64_tr_b16 v[242:243], v188 offset:22528
	s_waitcnt lgkmcnt(8)
	v_mfma_f32_32x32x16_bf16 v[64:79], v[218:221], v[148:151], v[64:79]
	v_exp_f32_e32 v106, v106
	v_exp_f32_e32 v107, v107
	ds_read_b64_tr_b16 v[180:181], v188 offset:20992
	ds_read_b64_tr_b16 v[182:183], v188 offset:23040
	v_mfma_f32_32x32x16_bf16 v[0:15], v[140:143], v[222:225], v[0:15]
	ds_read_b64_tr_b16 v[222:223], v188 offset:21504
	ds_read_b64_tr_b16 v[224:225], v188 offset:23552
	v_exp_f32_e32 v108, v108
	v_exp_f32_e32 v109, v109
	s_waitcnt lgkmcnt(10)
	v_mfma_f32_32x32x16_bf16 v[16:31], v[140:143], v[226:229], v[16:31]
	ds_read_b64_tr_b16 v[226:227], v188 offset:22016
	ds_read_b64_tr_b16 v[228:229], v188 offset:24064
	v_exp_f32_e32 v110, v110
	v_exp_f32_e32 v111, v111
	s_waitcnt lgkmcnt(10)
	v_mfma_f32_32x32x16_bf16 v[32:47], v[140:143], v[230:233], v[32:47]
	ds_read_b64_tr_b16 v[230:231], v188 offset:24576
	ds_read_b64_tr_b16 v[232:233], v188 offset:26624
	v_exp_f32_e32 v64, v64
	v_exp_f32_e32 v65, v65
	s_waitcnt lgkmcnt(10)
	v_mfma_f32_32x32x16_bf16 v[48:63], v[140:143], v[234:237], v[48:63]
	ds_read_b64_tr_b16 v[234:235], v188 offset:25088
	ds_read_b64_tr_b16 v[236:237], v188 offset:27136
	v_exp_f32_e32 v66, v66
	v_exp_f32_e32 v67, v67
	s_waitcnt lgkmcnt(10)
	v_mfma_f32_32x32x16_bf16 v[0:15], v[144:147], v[240:243], v[0:15]
	ds_read_b64_tr_b16 v[240:241], v188 offset:25600
	ds_read_b64_tr_b16 v[242:243], v188 offset:27648
	v_exp_f32_e32 v68, v68
	v_exp_f32_e32 v69, v69
	v_cvt_pk_bf16_f32 v140, v96, v97
	v_cvt_pk_bf16_f32 v142, v100, v101
	s_waitcnt lgkmcnt(10)
	v_mfma_f32_32x32x16_bf16 v[16:31], v[144:147], v[180:183], v[16:31]
	ds_read_b64_tr_b16 v[180:181], v188 offset:26112
	ds_read_b64_tr_b16 v[182:183], v188 offset:28160
	v_exp_f32_e32 v70, v70
	v_exp_f32_e32 v71, v71
	v_cvt_pk_bf16_f32 v141, v98, v99
	v_cvt_pk_bf16_f32 v143, v102, v103
	s_waitcnt lgkmcnt(10)
	v_mfma_f32_32x32x16_bf16 v[32:47], v[144:147], v[222:225], v[32:47]
	ds_read_b64_tr_b16 v[222:223], v188 offset:28672
	ds_read_b64_tr_b16 v[224:225], v188 offset:30720
	v_exp_f32_e32 v72, v72
	v_exp_f32_e32 v73, v73
	v_permlane32_swap_b32_e32 v140, v142
	s_waitcnt lgkmcnt(10)
	v_mfma_f32_32x32x16_bf16 v[48:63], v[144:147], v[226:229], v[48:63]
	ds_read_b64_tr_b16 v[226:227], v188 offset:29184
	ds_read_b64_tr_b16 v[228:229], v188 offset:31232
	v_exp_f32_e32 v74, v74
	v_exp_f32_e32 v75, v75
	v_permlane32_swap_b32_e32 v141, v143
	s_waitcnt lgkmcnt(10)
	v_mfma_f32_32x32x16_bf16 v[0:15], v[152:155], v[230:233], v[0:15]
	ds_read_b64_tr_b16 v[230:231], v188 offset:29696
	ds_read_b64_tr_b16 v[232:233], v188 offset:31744
	v_exp_f32_e32 v76, v76
	v_exp_f32_e32 v77, v77
	v_cvt_pk_bf16_f32 v144, v104, v105
	v_cvt_pk_bf16_f32 v146, v108, v109
	s_waitcnt lgkmcnt(10)
	v_mfma_f32_32x32x16_bf16 v[16:31], v[152:155], v[234:237], v[16:31]
	ds_read_b64_tr_b16 v[234:235], v188 offset:30208
	ds_read_b64_tr_b16 v[236:237], v188 offset:32256
	v_exp_f32_e32 v78, v78
	v_exp_f32_e32 v79, v79
	v_cvt_pk_bf16_f32 v145, v106, v107
	v_cvt_pk_bf16_f32 v147, v110, v111
	s_waitcnt vmcnt(6)
	s_barrier
; #define SBAR() __builtin_amdgcn_sched_barrier(0)
; #define SWAIT() asm volatile("s_waitcnt vmcnt(4)" ::: "memory")
; #define MASKLAST(P0, P1) do { _Pragma("unroll") for (int r = 8; r < 16; ++r) P0[r] = -1e30f; _Pragma("unroll") for (int r = 0; r < 16; ++r) P1[r] = -1e30f; } while (0)
; template <int D0> __device__ __forceinline__ void pv_one(f32x16& od, int vb, bf16x8 pa0, bf16x8 pa1, bf16x8 pa2, bf16x8 pa3) {
;   const s16x4 l0 = tr_read<v_rd_off(D0, 0, 0)>(vb), h0 = tr_read<v_rd_off(D0, 0, 1)>(vb), l1 = tr_read<v_rd_off(D0, 1, 0)>(vb), h1 = tr_read<v_rd_off(D0, 1, 1)>(vb);
;   const s16x4 l2 = tr_read<v_rd_off(D0, 2, 0)>(vb), h2 = tr_read<v_rd_off(D0, 2, 1)>(vb), l3 = tr_read<v_rd_off(D0, 3, 0)>(vb), h3 = tr_read<v_rd_off(D0, 3, 1)>(vb);
;   asm volatile("s_waitcnt lgkmcnt(0)" ::: "memory"); SBAR();
;     ...
;   od = __builtin_amdgcn_mfma_f32_32x32x16_bf16(pa0, PK(l0, h0), od, 0, 0, 0);
;   od = __builtin_amdgcn_mfma_f32_32x32x16_bf16(pa1, PK(l1, h1), od, 0, 0, 0);
;   od = __builtin_amdgcn_mfma_f32_32x32x16_bf16(pa2, PK(l2, h2), od, 0, 0, 0);
;   od = __builtin_amdgcn_mfma_f32_32x32x16_bf16(pa3, PK(l3, h3), od, 0, 0, 0);
;     ...
; }
; __device__ __forceinline__ void pv_d0(f32x16* o, int vb, bf16x8 pa0, bf16x8 pa1, bf16x8 pa2, bf16x8 pa3) {
;   pv_one<0>(o[0], vb, pa0, pa1, pa2, pa3); pv_one<1>(o[1], vb, pa0, pa1, pa2, pa3); pv_one<2>(o[2], vb, pa0, pa1, pa2, pa3); pv_one<3>(o[3], vb, pa0, pa1, pa2, pa3);
; }
; __device__ __forceinline__ void attn_unit_fast(const bf16* __restrict__ Qb, const bf16* __restrict__ Kh, const bf16* __restrict__ Vh, bf16* __restrict__ Ob, int NT, char* lds, int t0, const float* __restrict__ qg) {
;     ...
;   for (int j = 1; j + 1 < NT; j += 2) {
;     SBAR(); qkt(pB0, pB1, (bf16*)((char*)K_lds + SHM_K), qr, r32, hi);
;     finishSM_fast(pA0, pA1, l_reg, pa0, pa1, pa2, pa3); SBAR();
;     if (j + 2 < NT) SLOAD(SO, (j + 2) * KVBLK); SBAR();
;     pv_d0(o, vb0, pa0, pa1, pa2, pa3); partialSM_fast(pB0, pB1);
;     __syncthreads(); SWAIT(); SWRITE(0, SE);
;     __syncthreads();
;     SBAR(); qkt(pA0, pA1, K_lds, qr, r32, hi);
;     if (j + 2 == NT) MASKLAST(pA0, pA1);
;     finishSM_fast(pB0, pB1, l_reg, pa0, pa1, pa2, pa3); SBAR();
;     if (j + 3 < NT) SLOAD(SE, (j + 3) * KVBLK); SBAR();
;     pv_d0(o, vb0 + (int)SHM_V, pa0, pa1, pa2, pa3); partialSM_fast(pA0, pA1);
;     __syncthreads(); SWAIT(); SWRITE(1, SO);
;     __syncthreads();
;   }
	s_waitcnt lgkmcnt(10)
	v_mfma_f32_32x32x16_bf16 v[32:47], v[152:155], v[240:243], v[32:47]
	v_permlane32_swap_b32_e32 v144, v146
	s_add_u32 m0, s5, 0x0
	v_add_f32_e32 v238, v96, v97
	global_load_lds_dwordx4 v253, s[0:1]
	v_add_f32_e32 v238, v98, v238
	v_add_f32_e32 v238, v99, v238
	s_waitcnt lgkmcnt(8)
	v_mfma_f32_32x32x16_bf16 v[48:63], v[152:155], v[180:183], v[48:63]
	v_permlane32_swap_b32_e32 v145, v147
	s_add_u32 m0, s5, 0x2000
	v_add_f32_e32 v238, v100, v238
	global_load_lds_dwordx4 v254, s[0:1]
	v_add_f32_e32 v238, v101, v238
	v_add_f32_e32 v238, v102, v238
	s_add_u32 s0, s0, 0x4000
	s_addc_u32 s1, s1, 0
	s_waitcnt lgkmcnt(6)
	v_mfma_f32_32x32x16_bf16 v[0:15], v[156:159], v[222:225], v[0:15]
	v_add_f32_e32 v238, v103, v238
	v_add_f32_e32 v238, v104, v238
	v_add_f32_e32 v238, v105, v238
	ds_read_b128 v[206:209], v194 offset:49152
	s_waitcnt lgkmcnt(5)
	v_mfma_f32_32x32x16_bf16 v[16:31], v[156:159], v[226:229], v[16:31]
	v_add_f32_e32 v238, v106, v238
	v_add_f32_e32 v238, v107, v238
	v_add_f32_e32 v238, v108, v238
	ds_read_b128 v[210:213], v196 offset:49152
	s_waitcnt lgkmcnt(4)
	v_mfma_f32_32x32x16_bf16 v[32:47], v[156:159], v[230:233], v[32:47]
	v_add_f32_e32 v238, v109, v238
	v_add_f32_e32 v238, v110, v238
	ds_read_b128 v[214:217], v198 offset:49152
	s_waitcnt lgkmcnt(3)
	v_mfma_f32_32x32x16_bf16 v[48:63], v[156:159], v[234:237], v[48:63]
	v_add_f32_e32 v238, v111, v238
	v_add_f32_e32 v197, v238, v197
	ds_read_b128 v[218:221], v199 offset:49152
	s_waitcnt lgkmcnt(3)
	v_mfma_f32_32x32x16_bf16 v[160:175], v[206:209], v[112:115], 0
	ds_read_b128 v[206:209], v200 offset:49152
	v_cvt_pk_bf16_f32 v152, v64, v65
	v_cvt_pk_bf16_f32 v154, v68, v69
	v_add_f32_e32 v239, v64, v65
	v_add_f32_e32 v239, v66, v239
	s_waitcnt lgkmcnt(3)
	v_mfma_f32_32x32x16_bf16 v[160:175], v[210:213], v[116:119], v[160:175]
	ds_read_b128 v[210:213], v201 offset:49152
	v_cvt_pk_bf16_f32 v153, v66, v67
	v_cvt_pk_bf16_f32 v155, v70, v71
	v_add_f32_e32 v239, v67, v239
	v_add_f32_e32 v239, v68, v239
	s_waitcnt lgkmcnt(3)
	v_mfma_f32_32x32x16_bf16 v[160:175], v[214:217], v[120:123], v[160:175]
	ds_read_b128 v[214:217], v202 offset:49152
	v_permlane32_swap_b32_e32 v152, v154
	v_add_f32_e32 v239, v69, v239
	v_add_f32_e32 v239, v70, v239
	s_waitcnt lgkmcnt(3)
	v_mfma_f32_32x32x16_bf16 v[160:175], v[218:221], v[124:127], v[160:175]
	ds_read_b128 v[218:221], v203 offset:49152
	v_permlane32_swap_b32_e32 v153, v155
	v_add_f32_e32 v239, v71, v239
	v_add_f32_e32 v239, v72, v239
	s_waitcnt lgkmcnt(3)
	v_mfma_f32_32x32x16_bf16 v[160:175], v[206:209], v[128:131], v[160:175]
	ds_read_b128 v[206:209], v194 offset:57344
	v_cvt_pk_bf16_f32 v156, v72, v73
	v_cvt_pk_bf16_f32 v158, v76, v77
	v_add_f32_e32 v239, v73, v239
	v_add_f32_e32 v239, v74, v239
	s_barrier
	s_waitcnt lgkmcnt(3)
	v_mfma_f32_32x32x16_bf16 v[160:175], v[210:213], v[132:135], v[160:175]
	ds_read_b128 v[210:213], v196 offset:57344
	v_cvt_pk_bf16_f32 v157, v74, v75
	v_cvt_pk_bf16_f32 v159, v78, v79
	v_add_f32_e32 v239, v75, v239
	v_add_f32_e32 v239, v76, v239
	s_waitcnt lgkmcnt(3)
	v_mfma_f32_32x32x16_bf16 v[160:175], v[214:217], v[136:139], v[160:175]
	ds_read_b128 v[214:217], v198 offset:57344
	v_permlane32_swap_b32_e32 v156, v158
	v_add_f32_e32 v239, v77, v239
	v_add_f32_e32 v239, v78, v239
	s_waitcnt lgkmcnt(3)
	v_mfma_f32_32x32x16_bf16 v[160:175], v[218:221], v[148:151], v[160:175]
	ds_read_b128 v[218:221], v199 offset:57344
	v_permlane32_swap_b32_e32 v157, v159
	v_add_f32_e32 v239, v79, v239
	v_add_f32_e32 v197, v239, v197
	s_waitcnt lgkmcnt(3)
	v_mfma_f32_32x32x16_bf16 v[80:95], v[206:209], v[112:115], 0
	ds_read_b128 v[206:209], v200 offset:57344
	s_add_u32 m0, s5, 0x18800
	s_nop 0
	global_load_lds_dwordx4 v244, s[0:1]
	s_waitcnt lgkmcnt(3)
	v_mfma_f32_32x32x16_bf16 v[80:95], v[210:213], v[116:119], v[80:95]
	ds_read_b128 v[210:213], v201 offset:57344
	s_add_u32 m0, s5, 0x1a800
	s_nop 0
	global_load_lds_dwordx4 v245, s[0:1]
	s_waitcnt lgkmcnt(3)
	v_mfma_f32_32x32x16_bf16 v[80:95], v[214:217], v[120:123], v[80:95]
	ds_read_b128 v[214:217], v202 offset:57344
	v_exp_f32_e32 v160, v160
	v_exp_f32_e32 v161, v161
	ds_read_b64_tr_b16 v[222:223], v188 offset:32768
	ds_read_b64_tr_b16 v[224:225], v188 offset:34816
	s_waitcnt lgkmcnt(5)
	v_mfma_f32_32x32x16_bf16 v[80:95], v[218:221], v[124:127], v[80:95]
	ds_read_b128 v[218:221], v203 offset:57344
	v_exp_f32_e32 v162, v162
	v_exp_f32_e32 v163, v163
	ds_read_b64_tr_b16 v[226:227], v188 offset:33280
	ds_read_b64_tr_b16 v[228:229], v188 offset:35328
	s_waitcnt lgkmcnt(7)
	v_mfma_f32_32x32x16_bf16 v[80:95], v[206:209], v[128:131], v[80:95]
	v_exp_f32_e32 v164, v164
	v_exp_f32_e32 v165, v165
	ds_read_b64_tr_b16 v[230:231], v188 offset:33792
	ds_read_b64_tr_b16 v[232:233], v188 offset:35840
	s_waitcnt lgkmcnt(8)
	v_mfma_f32_32x32x16_bf16 v[80:95], v[210:213], v[132:135], v[80:95]
	v_exp_f32_e32 v166, v166
	v_exp_f32_e32 v167, v167
	ds_read_b64_tr_b16 v[234:235], v188 offset:34304
	ds_read_b64_tr_b16 v[236:237], v188 offset:36352
	s_waitcnt lgkmcnt(9)
	v_mfma_f32_32x32x16_bf16 v[80:95], v[214:217], v[136:139], v[80:95]
	v_exp_f32_e32 v168, v168
	v_exp_f32_e32 v169, v169
	ds_read_b64_tr_b16 v[240:241], v188 offset:36864
	ds_read_b64_tr_b16 v[242:243], v188 offset:38912
	s_waitcnt lgkmcnt(8)
	v_mfma_f32_32x32x16_bf16 v[80:95], v[218:221], v[148:151], v[80:95]
	v_exp_f32_e32 v170, v170
	v_exp_f32_e32 v171, v171
	ds_read_b64_tr_b16 v[180:181], v188 offset:37376
	ds_read_b64_tr_b16 v[182:183], v188 offset:39424
	v_mfma_f32_32x32x16_bf16 v[0:15], v[140:143], v[222:225], v[0:15]
	ds_read_b64_tr_b16 v[222:223], v188 offset:37888
	ds_read_b64_tr_b16 v[224:225], v188 offset:39936
	v_exp_f32_e32 v172, v172
	v_exp_f32_e32 v173, v173
	s_waitcnt lgkmcnt(10)
; #define SBAR() __builtin_amdgcn_sched_barrier(0)
; #define SWAIT() asm volatile("s_waitcnt vmcnt(4)" ::: "memory")
; #define MASKLAST(P0, P1) do { _Pragma("unroll") for (int r = 8; r < 16; ++r) P0[r] = -1e30f; _Pragma("unroll") for (int r = 0; r < 16; ++r) P1[r] = -1e30f; } while (0)
; template <int D0> __device__ __forceinline__ void pv_one(f32x16& od, int vb, bf16x8 pa0, bf16x8 pa1, bf16x8 pa2, bf16x8 pa3) {
;   const s16x4 l0 = tr_read<v_rd_off(D0, 0, 0)>(vb), h0 = tr_read<v_rd_off(D0, 0, 1)>(vb), l1 = tr_read<v_rd_off(D0, 1, 0)>(vb), h1 = tr_read<v_rd_off(D0, 1, 1)>(vb);
;   const s16x4 l2 = tr_read<v_rd_off(D0, 2, 0)>(vb), h2 = tr_read<v_rd_off(D0, 2, 1)>(vb), l3 = tr_read<v_rd_off(D0, 3, 0)>(vb), h3 = tr_read<v_rd_off(D0, 3, 1)>(vb);
;   asm volatile("s_waitcnt lgkmcnt(0)" ::: "memory"); SBAR();
;     ...
;   od = __builtin_amdgcn_mfma_f32_32x32x16_bf16(pa0, PK(l0, h0), od, 0, 0, 0);
;   od = __builtin_amdgcn_mfma_f32_32x32x16_bf16(pa1, PK(l1, h1), od, 0, 0, 0);
;   od = __builtin_amdgcn_mfma_f32_32x32x16_bf16(pa2, PK(l2, h2), od, 0, 0, 0);
;   od = __builtin_amdgcn_mfma_f32_32x32x16_bf16(pa3, PK(l3, h3), od, 0, 0, 0);
;     ...
; }
; __device__ __forceinline__ void pv_d0(f32x16* o, int vb, bf16x8 pa0, bf16x8 pa1, bf16x8 pa2, bf16x8 pa3) {
;   pv_one<0>(o[0], vb, pa0, pa1, pa2, pa3); pv_one<1>(o[1], vb, pa0, pa1, pa2, pa3); pv_one<2>(o[2], vb, pa0, pa1, pa2, pa3); pv_one<3>(o[3], vb, pa0, pa1, pa2, pa3);
; }
; __device__ __forceinline__ void attn_unit_fast(const bf16* __restrict__ Qb, const bf16* __restrict__ Kh, const bf16* __restrict__ Vh, bf16* __restrict__ Ob, int NT, char* lds, int t0, const float* __restrict__ qg) {
;     ...
;   for (int j = 1; j + 1 < NT; j += 2) {
;     SBAR(); qkt(pB0, pB1, (bf16*)((char*)K_lds + SHM_K), qr, r32, hi);
;     finishSM_fast(pA0, pA1, l_reg, pa0, pa1, pa2, pa3); SBAR();
;     if (j + 2 < NT) SLOAD(SO, (j + 2) * KVBLK); SBAR();
;     pv_d0(o, vb0, pa0, pa1, pa2, pa3); partialSM_fast(pB0, pB1);
;     __syncthreads(); SWAIT(); SWRITE(0, SE);
;     __syncthreads();
;     SBAR(); qkt(pA0, pA1, K_lds, qr, r32, hi);
;     if (j + 2 == NT) MASKLAST(pA0, pA1);
;     finishSM_fast(pB0, pB1, l_reg, pa0, pa1, pa2, pa3); SBAR();
;     if (j + 3 < NT) SLOAD(SE, (j + 3) * KVBLK); SBAR();
;     pv_d0(o, vb0 + (int)SHM_V, pa0, pa1, pa2, pa3); partialSM_fast(pA0, pA1);
;     __syncthreads(); SWAIT(); SWRITE(1, SO);
;     __syncthreads();
;   }
	v_mfma_f32_32x32x16_bf16 v[16:31], v[140:143], v[226:229], v[16:31]
	ds_read_b64_tr_b16 v[226:227], v188 offset:38400
	ds_read_b64_tr_b16 v[228:229], v188 offset:40448
	v_exp_f32_e32 v174, v174
	v_exp_f32_e32 v175, v175
	s_waitcnt lgkmcnt(10)
	v_mfma_f32_32x32x16_bf16 v[32:47], v[140:143], v[230:233], v[32:47]
	ds_read_b64_tr_b16 v[230:231], v188 offset:40960
	ds_read_b64_tr_b16 v[232:233], v188 offset:43008
	v_exp_f32_e32 v80, v80
	v_exp_f32_e32 v81, v81
	s_waitcnt lgkmcnt(10)
	v_mfma_f32_32x32x16_bf16 v[48:63], v[140:143], v[234:237], v[48:63]
	ds_read_b64_tr_b16 v[234:235], v188 offset:41472
	ds_read_b64_tr_b16 v[236:237], v188 offset:43520
	v_exp_f32_e32 v82, v82
	v_exp_f32_e32 v83, v83
	s_waitcnt lgkmcnt(10)
	v_mfma_f32_32x32x16_bf16 v[0:15], v[144:147], v[240:243], v[0:15]
	ds_read_b64_tr_b16 v[240:241], v188 offset:41984
	ds_read_b64_tr_b16 v[242:243], v188 offset:44032
	v_exp_f32_e32 v84, v84
	v_exp_f32_e32 v85, v85
	v_cvt_pk_bf16_f32 v140, v160, v161
	v_cvt_pk_bf16_f32 v142, v164, v165
	s_waitcnt lgkmcnt(10)
	v_mfma_f32_32x32x16_bf16 v[16:31], v[144:147], v[180:183], v[16:31]
	ds_read_b64_tr_b16 v[180:181], v188 offset:42496
	ds_read_b64_tr_b16 v[182:183], v188 offset:44544
	v_exp_f32_e32 v86, v86
	v_exp_f32_e32 v87, v87
	v_cvt_pk_bf16_f32 v141, v162, v163
	v_cvt_pk_bf16_f32 v143, v166, v167
	s_waitcnt lgkmcnt(10)
	v_mfma_f32_32x32x16_bf16 v[32:47], v[144:147], v[222:225], v[32:47]
	ds_read_b64_tr_b16 v[222:223], v188 offset:45056
	ds_read_b64_tr_b16 v[224:225], v188 offset:47104
	v_exp_f32_e32 v88, v88
	v_exp_f32_e32 v89, v89
	v_permlane32_swap_b32_e32 v140, v142
	s_waitcnt lgkmcnt(10)
	v_mfma_f32_32x32x16_bf16 v[48:63], v[144:147], v[226:229], v[48:63]
	ds_read_b64_tr_b16 v[226:227], v188 offset:45568
	ds_read_b64_tr_b16 v[228:229], v188 offset:47616
	v_exp_f32_e32 v90, v90
	v_exp_f32_e32 v91, v91
	v_permlane32_swap_b32_e32 v141, v143
	s_waitcnt lgkmcnt(10)
	v_mfma_f32_32x32x16_bf16 v[0:15], v[152:155], v[230:233], v[0:15]
	ds_read_b64_tr_b16 v[230:231], v188 offset:46080
	ds_read_b64_tr_b16 v[232:233], v188 offset:48128
	v_exp_f32_e32 v92, v92
	v_exp_f32_e32 v93, v93
	v_cvt_pk_bf16_f32 v144, v168, v169
	v_cvt_pk_bf16_f32 v146, v172, v173
	s_waitcnt lgkmcnt(10)
	v_mfma_f32_32x32x16_bf16 v[16:31], v[152:155], v[234:237], v[16:31]
	ds_read_b64_tr_b16 v[234:235], v188 offset:46592
	ds_read_b64_tr_b16 v[236:237], v188 offset:48640
	v_exp_f32_e32 v94, v94
	v_exp_f32_e32 v95, v95
	v_cvt_pk_bf16_f32 v145, v170, v171
	v_cvt_pk_bf16_f32 v147, v174, v175
	s_waitcnt vmcnt(6)
	s_barrier
	s_waitcnt lgkmcnt(10)
	v_mfma_f32_32x32x16_bf16 v[32:47], v[152:155], v[240:243], v[32:47]
	v_permlane32_swap_b32_e32 v144, v146
	s_add_u32 m0, s5, 0x4000
	v_add_f32_e32 v238, v160, v161
	global_load_lds_dwordx4 v253, s[0:1]
	v_add_f32_e32 v238, v162, v238
	v_add_f32_e32 v238, v163, v238
	s_waitcnt lgkmcnt(8)
	v_mfma_f32_32x32x16_bf16 v[48:63], v[152:155], v[180:183], v[48:63]
	v_permlane32_swap_b32_e32 v145, v147
	s_add_u32 m0, s5, 0x6000
	v_add_f32_e32 v238, v164, v238
	global_load_lds_dwordx4 v254, s[0:1]
	v_add_f32_e32 v238, v165, v238
	v_add_f32_e32 v238, v166, v238
	s_add_u32 s0, s0, 0x4000
	s_addc_u32 s1, s1, 0
	s_waitcnt lgkmcnt(6)
	v_mfma_f32_32x32x16_bf16 v[0:15], v[156:159], v[222:225], v[0:15]
	v_add_f32_e32 v238, v167, v238
	v_add_f32_e32 v238, v168, v238
	v_add_f32_e32 v238, v169, v238
	ds_read_b128 v[206:209], v194
	s_waitcnt lgkmcnt(5)
	v_mfma_f32_32x32x16_bf16 v[16:31], v[156:159], v[226:229], v[16:31]
	v_add_f32_e32 v238, v170, v238
	v_add_f32_e32 v238, v171, v238
	v_add_f32_e32 v238, v172, v238
	ds_read_b128 v[210:213], v196
	s_waitcnt lgkmcnt(4)
	v_mfma_f32_32x32x16_bf16 v[32:47], v[156:159], v[230:233], v[32:47]
	v_add_f32_e32 v238, v173, v238
	v_add_f32_e32 v238, v174, v238
	ds_read_b128 v[214:217], v198
	s_waitcnt lgkmcnt(3)
	v_mfma_f32_32x32x16_bf16 v[48:63], v[156:159], v[234:237], v[48:63]
	v_add_f32_e32 v238, v175, v238
	v_add_f32_e32 v197, v238, v197
	ds_read_b128 v[218:221], v199
	s_waitcnt lgkmcnt(3)
	v_mfma_f32_32x32x16_bf16 v[96:111], v[206:209], v[112:115], 0
	ds_read_b128 v[206:209], v200
	v_cvt_pk_bf16_f32 v152, v80, v81
	v_cvt_pk_bf16_f32 v154, v84, v85
	v_add_f32_e32 v239, v80, v81
	v_add_f32_e32 v239, v82, v239
	s_waitcnt lgkmcnt(3)
	v_mfma_f32_32x32x16_bf16 v[96:111], v[210:213], v[116:119], v[96:111]
	ds_read_b128 v[210:213], v201
	v_cvt_pk_bf16_f32 v153, v82, v83
	v_cvt_pk_bf16_f32 v155, v86, v87
	v_add_f32_e32 v239, v83, v239
	v_add_f32_e32 v239, v84, v239
	s_waitcnt lgkmcnt(3)
	v_mfma_f32_32x32x16_bf16 v[96:111], v[214:217], v[120:123], v[96:111]
	ds_read_b128 v[214:217], v202
	v_permlane32_swap_b32_e32 v152, v154
	v_add_f32_e32 v239, v85, v239
	v_add_f32_e32 v239, v86, v239
	s_waitcnt lgkmcnt(3)
	v_mfma_f32_32x32x16_bf16 v[96:111], v[218:221], v[124:127], v[96:111]
	ds_read_b128 v[218:221], v203
	v_permlane32_swap_b32_e32 v153, v155
	v_add_f32_e32 v239, v87, v239
	v_add_f32_e32 v239, v88, v239
	s_waitcnt lgkmcnt(3)
	v_mfma_f32_32x32x16_bf16 v[96:111], v[206:209], v[128:131], v[96:111]
	ds_read_b128 v[206:209], v194 offset:8192
	v_cvt_pk_bf16_f32 v156, v88, v89
	v_cvt_pk_bf16_f32 v158, v92, v93
	v_add_f32_e32 v239, v89, v239
	v_add_f32_e32 v239, v90, v239
	s_barrier
; #define SBAR() __builtin_amdgcn_sched_barrier(0)
; #define SWAIT() asm volatile("s_waitcnt vmcnt(4)" ::: "memory")
; #define MASKLAST(P0, P1) do { _Pragma("unroll") for (int r = 8; r < 16; ++r) P0[r] = -1e30f; _Pragma("unroll") for (int r = 0; r < 16; ++r) P1[r] = -1e30f; } while (0)
; template <int D0> __device__ __forceinline__ void pv_one(f32x16& od, int vb, bf16x8 pa0, bf16x8 pa1, bf16x8 pa2, bf16x8 pa3) {
;   const s16x4 l0 = tr_read<v_rd_off(D0, 0, 0)>(vb), h0 = tr_read<v_rd_off(D0, 0, 1)>(vb), l1 = tr_read<v_rd_off(D0, 1, 0)>(vb), h1 = tr_read<v_rd_off(D0, 1, 1)>(vb);
;   const s16x4 l2 = tr_read<v_rd_off(D0, 2, 0)>(vb), h2 = tr_read<v_rd_off(D0, 2, 1)>(vb), l3 = tr_read<v_rd_off(D0, 3, 0)>(vb), h3 = tr_read<v_rd_off(D0, 3, 1)>(vb);
;   asm volatile("s_waitcnt lgkmcnt(0)" ::: "memory"); SBAR();
;     ...
;   od = __builtin_amdgcn_mfma_f32_32x32x16_bf16(pa0, PK(l0, h0), od, 0, 0, 0);
;   od = __builtin_amdgcn_mfma_f32_32x32x16_bf16(pa1, PK(l1, h1), od, 0, 0, 0);
;   od = __builtin_amdgcn_mfma_f32_32x32x16_bf16(pa2, PK(l2, h2), od, 0, 0, 0);
;   od = __builtin_amdgcn_mfma_f32_32x32x16_bf16(pa3, PK(l3, h3), od, 0, 0, 0);
;     ...
; }
; __device__ __forceinline__ void pv_d0(f32x16* o, int vb, bf16x8 pa0, bf16x8 pa1, bf16x8 pa2, bf16x8 pa3) {
;   pv_one<0>(o[0], vb, pa0, pa1, pa2, pa3); pv_one<1>(o[1], vb, pa0, pa1, pa2, pa3); pv_one<2>(o[2], vb, pa0, pa1, pa2, pa3); pv_one<3>(o[3], vb, pa0, pa1, pa2, pa3);
; }
; __device__ __forceinline__ void attn_unit_fast(const bf16* __restrict__ Qb, const bf16* __restrict__ Kh, const bf16* __restrict__ Vh, bf16* __restrict__ Ob, int NT, char* lds, int t0, const float* __restrict__ qg) {
;     ...
;   for (int j = 1; j + 1 < NT; j += 2) {
;     SBAR(); qkt(pB0, pB1, (bf16*)((char*)K_lds + SHM_K), qr, r32, hi);
;     finishSM_fast(pA0, pA1, l_reg, pa0, pa1, pa2, pa3); SBAR();
;     if (j + 2 < NT) SLOAD(SO, (j + 2) * KVBLK); SBAR();
;     pv_d0(o, vb0, pa0, pa1, pa2, pa3); partialSM_fast(pB0, pB1);
;     __syncthreads(); SWAIT(); SWRITE(0, SE);
;     __syncthreads();
;     SBAR(); qkt(pA0, pA1, K_lds, qr, r32, hi);
;     if (j + 2 == NT) MASKLAST(pA0, pA1);
;     finishSM_fast(pB0, pB1, l_reg, pa0, pa1, pa2, pa3); SBAR();
;     if (j + 3 < NT) SLOAD(SE, (j + 3) * KVBLK); SBAR();
;     pv_d0(o, vb0 + (int)SHM_V, pa0, pa1, pa2, pa3); partialSM_fast(pA0, pA1);
;     __syncthreads(); SWAIT(); SWRITE(1, SO);
;     __syncthreads();
;   }
	s_waitcnt lgkmcnt(3)
	v_mfma_f32_32x32x16_bf16 v[96:111], v[210:213], v[132:135], v[96:111]
	ds_read_b128 v[210:213], v196 offset:8192
	v_cvt_pk_bf16_f32 v157, v90, v91
	v_cvt_pk_bf16_f32 v159, v94, v95
	v_add_f32_e32 v239, v91, v239
	v_add_f32_e32 v239, v92, v239
	s_waitcnt lgkmcnt(3)
	v_mfma_f32_32x32x16_bf16 v[96:111], v[214:217], v[136:139], v[96:111]
	ds_read_b128 v[214:217], v198 offset:8192
	v_permlane32_swap_b32_e32 v156, v158
	v_add_f32_e32 v239, v93, v239
	v_add_f32_e32 v239, v94, v239
	s_waitcnt lgkmcnt(3)
	v_mfma_f32_32x32x16_bf16 v[96:111], v[218:221], v[148:151], v[96:111]
	ds_read_b128 v[218:221], v199 offset:8192
	v_permlane32_swap_b32_e32 v157, v159
	v_add_f32_e32 v239, v95, v239
	v_add_f32_e32 v197, v239, v197
	s_waitcnt lgkmcnt(3)
	v_mfma_f32_32x32x16_bf16 v[64:79], v[206:209], v[112:115], 0
	ds_read_b128 v[206:209], v200 offset:8192
	s_add_u32 m0, s5, 0x1c800
	s_nop 0
	global_load_lds_dwordx4 v244, s[0:1]
	s_waitcnt lgkmcnt(3)
	v_mfma_f32_32x32x16_bf16 v[64:79], v[210:213], v[116:119], v[64:79]
	ds_read_b128 v[210:213], v201 offset:8192
	s_add_u32 m0, s5, 0x1e800
	s_nop 0
	global_load_lds_dwordx4 v245, s[0:1]
	s_waitcnt lgkmcnt(3)
	v_mfma_f32_32x32x16_bf16 v[64:79], v[214:217], v[120:123], v[64:79]
	ds_read_b128 v[214:217], v202 offset:8192
	v_exp_f32_e32 v96, v96
	v_exp_f32_e32 v97, v97
	ds_read_b64_tr_b16 v[222:223], v188 offset:49152
	ds_read_b64_tr_b16 v[224:225], v188 offset:51200
	s_waitcnt lgkmcnt(5)
	v_mfma_f32_32x32x16_bf16 v[64:79], v[218:221], v[124:127], v[64:79]
	ds_read_b128 v[218:221], v203 offset:8192
	v_exp_f32_e32 v98, v98
	v_exp_f32_e32 v99, v99
	ds_read_b64_tr_b16 v[226:227], v188 offset:49664
	ds_read_b64_tr_b16 v[228:229], v188 offset:51712
	s_waitcnt lgkmcnt(7)
	v_mfma_f32_32x32x16_bf16 v[64:79], v[206:209], v[128:131], v[64:79]
	v_exp_f32_e32 v100, v100
	v_exp_f32_e32 v101, v101
	ds_read_b64_tr_b16 v[230:231], v188 offset:50176
	ds_read_b64_tr_b16 v[232:233], v188 offset:52224
	s_waitcnt lgkmcnt(8)
	v_mfma_f32_32x32x16_bf16 v[64:79], v[210:213], v[132:135], v[64:79]
	v_exp_f32_e32 v102, v102
	v_exp_f32_e32 v103, v103
	ds_read_b64_tr_b16 v[234:235], v188 offset:50688
	ds_read_b64_tr_b16 v[236:237], v188 offset:52736
	s_waitcnt lgkmcnt(9)
	v_mfma_f32_32x32x16_bf16 v[64:79], v[214:217], v[136:139], v[64:79]
	v_exp_f32_e32 v104, v104
	v_exp_f32_e32 v105, v105
	ds_read_b64_tr_b16 v[240:241], v188 offset:53248
	ds_read_b64_tr_b16 v[242:243], v188 offset:55296
	s_waitcnt lgkmcnt(8)
	v_mfma_f32_32x32x16_bf16 v[64:79], v[218:221], v[148:151], v[64:79]
	v_exp_f32_e32 v106, v106
	v_exp_f32_e32 v107, v107
	ds_read_b64_tr_b16 v[180:181], v188 offset:53760
	ds_read_b64_tr_b16 v[182:183], v188 offset:55808
	v_mfma_f32_32x32x16_bf16 v[0:15], v[140:143], v[222:225], v[0:15]
	ds_read_b64_tr_b16 v[222:223], v188 offset:54272
	ds_read_b64_tr_b16 v[224:225], v188 offset:56320
	v_exp_f32_e32 v108, v108
	v_exp_f32_e32 v109, v109
	s_waitcnt lgkmcnt(10)
	v_mfma_f32_32x32x16_bf16 v[16:31], v[140:143], v[226:229], v[16:31]
	ds_read_b64_tr_b16 v[226:227], v188 offset:54784
	ds_read_b64_tr_b16 v[228:229], v188 offset:56832
	v_exp_f32_e32 v110, v110
	v_exp_f32_e32 v111, v111
	s_waitcnt lgkmcnt(10)
	v_mfma_f32_32x32x16_bf16 v[32:47], v[140:143], v[230:233], v[32:47]
	ds_read_b64_tr_b16 v[230:231], v188 offset:57344
	ds_read_b64_tr_b16 v[232:233], v188 offset:59392
	v_exp_f32_e32 v64, v64
	v_exp_f32_e32 v65, v65
	s_waitcnt lgkmcnt(10)
	v_mfma_f32_32x32x16_bf16 v[48:63], v[140:143], v[234:237], v[48:63]
	ds_read_b64_tr_b16 v[234:235], v188 offset:57856
	ds_read_b64_tr_b16 v[236:237], v188 offset:59904
	v_exp_f32_e32 v66, v66
	v_exp_f32_e32 v67, v67
	s_waitcnt lgkmcnt(10)
	v_mfma_f32_32x32x16_bf16 v[0:15], v[144:147], v[240:243], v[0:15]
	ds_read_b64_tr_b16 v[240:241], v188 offset:58368
	ds_read_b64_tr_b16 v[242:243], v188 offset:60416
	v_exp_f32_e32 v68, v68
	v_exp_f32_e32 v69, v69
	v_cvt_pk_bf16_f32 v140, v96, v97
	v_cvt_pk_bf16_f32 v142, v100, v101
	s_waitcnt lgkmcnt(10)
	v_mfma_f32_32x32x16_bf16 v[16:31], v[144:147], v[180:183], v[16:31]
	ds_read_b64_tr_b16 v[180:181], v188 offset:58880
	ds_read_b64_tr_b16 v[182:183], v188 offset:60928
	v_exp_f32_e32 v70, v70
	v_exp_f32_e32 v71, v71
	v_cvt_pk_bf16_f32 v141, v98, v99
	v_cvt_pk_bf16_f32 v143, v102, v103
	s_waitcnt lgkmcnt(10)
	v_mfma_f32_32x32x16_bf16 v[32:47], v[144:147], v[222:225], v[32:47]
	ds_read_b64_tr_b16 v[222:223], v188 offset:61440
	ds_read_b64_tr_b16 v[224:225], v188 offset:63488
	v_exp_f32_e32 v72, v72
	v_exp_f32_e32 v73, v73
	v_permlane32_swap_b32_e32 v140, v142
	s_waitcnt lgkmcnt(10)
	v_mfma_f32_32x32x16_bf16 v[48:63], v[144:147], v[226:229], v[48:63]
	ds_read_b64_tr_b16 v[226:227], v188 offset:61952
	ds_read_b64_tr_b16 v[228:229], v188 offset:64000
	v_exp_f32_e32 v74, v74
	v_exp_f32_e32 v75, v75
	v_permlane32_swap_b32_e32 v141, v143
	s_waitcnt lgkmcnt(10)
	v_mfma_f32_32x32x16_bf16 v[0:15], v[152:155], v[230:233], v[0:15]
	ds_read_b64_tr_b16 v[230:231], v188 offset:62464
	ds_read_b64_tr_b16 v[232:233], v188 offset:64512
	v_exp_f32_e32 v76, v76
	v_exp_f32_e32 v77, v77
	v_cvt_pk_bf16_f32 v144, v104, v105
	v_cvt_pk_bf16_f32 v146, v108, v109
	s_waitcnt lgkmcnt(10)
	v_mfma_f32_32x32x16_bf16 v[16:31], v[152:155], v[234:237], v[16:31]
	ds_read_b64_tr_b16 v[234:235], v188 offset:62976
	ds_read_b64_tr_b16 v[236:237], v188 offset:65024
	v_exp_f32_e32 v78, v78
	v_exp_f32_e32 v79, v79
	v_cvt_pk_bf16_f32 v145, v106, v107
	v_cvt_pk_bf16_f32 v147, v110, v111
	s_waitcnt vmcnt(6)
	s_barrier
; #define SBAR() __builtin_amdgcn_sched_barrier(0)
; template <int D0> __device__ __forceinline__ void pv_one(f32x16& od, int vb, bf16x8 pa0, bf16x8 pa1, bf16x8 pa2, bf16x8 pa3) {
;   const s16x4 l0 = tr_read<v_rd_off(D0, 0, 0)>(vb), h0 = tr_read<v_rd_off(D0, 0, 1)>(vb), l1 = tr_read<v_rd_off(D0, 1, 0)>(vb), h1 = tr_read<v_rd_off(D0, 1, 1)>(vb);
;   const s16x4 l2 = tr_read<v_rd_off(D0, 2, 0)>(vb), h2 = tr_read<v_rd_off(D0, 2, 1)>(vb), l3 = tr_read<v_rd_off(D0, 3, 0)>(vb), h3 = tr_read<v_rd_off(D0, 3, 1)>(vb);
;   asm volatile("s_waitcnt lgkmcnt(0)" ::: "memory"); SBAR();
;     ...
;   od = __builtin_amdgcn_mfma_f32_32x32x16_bf16(pa0, PK(l0, h0), od, 0, 0, 0);
;   od = __builtin_amdgcn_mfma_f32_32x32x16_bf16(pa1, PK(l1, h1), od, 0, 0, 0);
;   od = __builtin_amdgcn_mfma_f32_32x32x16_bf16(pa2, PK(l2, h2), od, 0, 0, 0);
;   od = __builtin_amdgcn_mfma_f32_32x32x16_bf16(pa3, PK(l3, h3), od, 0, 0, 0);
;     ...
; }
; __device__ __forceinline__ void pv_d0(f32x16* o, int vb, bf16x8 pa0, bf16x8 pa1, bf16x8 pa2, bf16x8 pa3) {
;   pv_one<0>(o[0], vb, pa0, pa1, pa2, pa3); pv_one<1>(o[1], vb, pa0, pa1, pa2, pa3); pv_one<2>(o[2], vb, pa0, pa1, pa2, pa3); pv_one<3>(o[3], vb, pa0, pa1, pa2, pa3);
; }
; __device__ __forceinline__ void attn_unit_fast(const bf16* __restrict__ Qb, const bf16* __restrict__ Kh, const bf16* __restrict__ Vh, bf16* __restrict__ Ob, int NT, char* lds, int t0, const float* __restrict__ qg) {
;     ...
;   finishSM_fast(pA0, pA1, l_reg, pa0, pa1, pa2, pa3); SBAR();
;   pv_d0(o, vb0, pa0, pa1, pa2, pa3);
;   { int r32e = r32; asm volatile("" : "+v"(r32e)); if (hi == 0) li_l[r32e] = l_reg; }
;   asm volatile("s_waitcnt lgkmcnt(0)" ::: "memory");
	s_waitcnt lgkmcnt(10)
	v_mfma_f32_32x32x16_bf16 v[32:47], v[152:155], v[240:243], v[32:47]
	v_permlane32_swap_b32_e32 v144, v146
	s_add_u32 m0, s5, 0x8000
	v_add_f32_e32 v238, v96, v97
	global_load_lds_dwordx4 v253, s[0:1]
	v_add_f32_e32 v238, v98, v238
	v_add_f32_e32 v238, v99, v238
	s_waitcnt lgkmcnt(8)
	v_mfma_f32_32x32x16_bf16 v[48:63], v[152:155], v[180:183], v[48:63]
	v_permlane32_swap_b32_e32 v145, v147
	s_add_u32 m0, s5, 0xa000
	v_add_f32_e32 v238, v100, v238
	global_load_lds_dwordx4 v254, s[0:1]
	v_add_f32_e32 v238, v101, v238
	v_add_f32_e32 v238, v102, v238
	s_add_u32 s0, s0, 0x4000
	s_addc_u32 s1, s1, 0
	s_waitcnt lgkmcnt(6)
	v_mfma_f32_32x32x16_bf16 v[0:15], v[156:159], v[222:225], v[0:15]
	v_add_f32_e32 v238, v103, v238
	v_add_f32_e32 v238, v104, v238
	v_add_f32_e32 v238, v105, v238
	ds_read_b128 v[206:209], v194 offset:16384
	s_waitcnt lgkmcnt(5)
	v_mfma_f32_32x32x16_bf16 v[16:31], v[156:159], v[226:229], v[16:31]
	v_add_f32_e32 v238, v106, v238
	v_add_f32_e32 v238, v107, v238
	v_add_f32_e32 v238, v108, v238
	ds_read_b128 v[210:213], v196 offset:16384
	s_waitcnt lgkmcnt(4)
	v_mfma_f32_32x32x16_bf16 v[32:47], v[156:159], v[230:233], v[32:47]
	v_add_f32_e32 v238, v109, v238
	v_add_f32_e32 v238, v110, v238
	ds_read_b128 v[214:217], v198 offset:16384
	s_waitcnt lgkmcnt(3)
	v_mfma_f32_32x32x16_bf16 v[48:63], v[156:159], v[234:237], v[48:63]
	v_add_f32_e32 v238, v111, v238
	v_add_f32_e32 v197, v238, v197
	ds_read_b128 v[218:221], v199 offset:16384
	s_sub_u32 s4, s4, 1
	s_cmp_lg_u32 s4, 0
	s_cbranch_scc1 .Lattn_loop
	v_cvt_pk_bf16_f32 v152, v64, v65
	v_cvt_pk_bf16_f32 v154, v68, v69
	v_cvt_pk_bf16_f32 v153, v66, v67
	v_cvt_pk_bf16_f32 v155, v70, v71
	s_nop 1
	v_permlane32_swap_b32_e32 v152, v154
	s_nop 1
	v_permlane32_swap_b32_e32 v153, v155
	v_cvt_pk_bf16_f32 v156, v72, v73
	v_cvt_pk_bf16_f32 v158, v76, v77
	v_cvt_pk_bf16_f32 v157, v74, v75
	v_cvt_pk_bf16_f32 v159, v78, v79
	s_nop 1
	v_permlane32_swap_b32_e32 v156, v158
	s_nop 1
	v_permlane32_swap_b32_e32 v157, v159
	v_add_f32_e32 v239, v64, v65
	v_add_f32_e32 v239, v66, v239
	v_add_f32_e32 v239, v67, v239
	v_add_f32_e32 v239, v68, v239
	v_add_f32_e32 v239, v69, v239
	v_add_f32_e32 v239, v70, v239
	v_add_f32_e32 v239, v71, v239
	v_add_f32_e32 v239, v72, v239
	v_add_f32_e32 v239, v73, v239
	v_add_f32_e32 v239, v74, v239
	v_add_f32_e32 v239, v75, v239
	v_add_f32_e32 v239, v76, v239
	v_add_f32_e32 v239, v77, v239
	v_add_f32_e32 v239, v78, v239
	v_add_f32_e32 v239, v79, v239
	v_add_f32_e32 v197, v239, v197
	ds_read_b64_tr_b16 v[222:223], v188
	ds_read_b64_tr_b16 v[224:225], v188 offset:2048
	ds_read_b64_tr_b16 v[226:227], v188 offset:512
	ds_read_b64_tr_b16 v[228:229], v188 offset:2560
	ds_read_b64_tr_b16 v[230:231], v188 offset:1024
	ds_read_b64_tr_b16 v[232:233], v188 offset:3072
	ds_read_b64_tr_b16 v[234:235], v188 offset:1536
	ds_read_b64_tr_b16 v[236:237], v188 offset:3584
	ds_read_b64_tr_b16 v[240:241], v188 offset:4096
	ds_read_b64_tr_b16 v[242:243], v188 offset:6144
	ds_read_b64_tr_b16 v[180:181], v188 offset:4608
	ds_read_b64_tr_b16 v[182:183], v188 offset:6656
	s_waitcnt lgkmcnt(10)
	v_mfma_f32_32x32x16_bf16 v[0:15], v[140:143], v[222:225], v[0:15]
	ds_read_b64_tr_b16 v[222:223], v188 offset:5120
	ds_read_b64_tr_b16 v[224:225], v188 offset:7168
	s_waitcnt lgkmcnt(10)
	v_mfma_f32_32x32x16_bf16 v[16:31], v[140:143], v[226:229], v[16:31]
	ds_read_b64_tr_b16 v[226:227], v188 offset:5632
	ds_read_b64_tr_b16 v[228:229], v188 offset:7680
	s_waitcnt lgkmcnt(10)
	v_mfma_f32_32x32x16_bf16 v[32:47], v[140:143], v[230:233], v[32:47]
	ds_read_b64_tr_b16 v[230:231], v188 offset:8192
	ds_read_b64_tr_b16 v[232:233], v188 offset:10240
	s_waitcnt lgkmcnt(10)
	v_mfma_f32_32x32x16_bf16 v[48:63], v[140:143], v[234:237], v[48:63]
	ds_read_b64_tr_b16 v[234:235], v188 offset:8704
	ds_read_b64_tr_b16 v[236:237], v188 offset:10752
	s_waitcnt lgkmcnt(10)
	v_mfma_f32_32x32x16_bf16 v[0:15], v[144:147], v[240:243], v[0:15]
	ds_read_b64_tr_b16 v[240:241], v188 offset:9216
	ds_read_b64_tr_b16 v[242:243], v188 offset:11264
	s_waitcnt lgkmcnt(10)
	v_mfma_f32_32x32x16_bf16 v[16:31], v[144:147], v[180:183], v[16:31]
	ds_read_b64_tr_b16 v[180:181], v188 offset:9728
	ds_read_b64_tr_b16 v[182:183], v188 offset:11776
	s_waitcnt lgkmcnt(10)
	v_mfma_f32_32x32x16_bf16 v[32:47], v[144:147], v[222:225], v[32:47]
	ds_read_b64_tr_b16 v[222:223], v188 offset:12288
	ds_read_b64_tr_b16 v[224:225], v188 offset:14336
	s_waitcnt lgkmcnt(10)
	v_mfma_f32_32x32x16_bf16 v[48:63], v[144:147], v[226:229], v[48:63]
	ds_read_b64_tr_b16 v[226:227], v188 offset:12800
	ds_read_b64_tr_b16 v[228:229], v188 offset:14848
	s_waitcnt lgkmcnt(10)
	v_mfma_f32_32x32x16_bf16 v[0:15], v[152:155], v[230:233], v[0:15]
	ds_read_b64_tr_b16 v[230:231], v188 offset:13312
	ds_read_b64_tr_b16 v[232:233], v188 offset:15360
	s_waitcnt lgkmcnt(10)
	v_mfma_f32_32x32x16_bf16 v[16:31], v[152:155], v[234:237], v[16:31]
	ds_read_b64_tr_b16 v[234:235], v188 offset:13824
	ds_read_b64_tr_b16 v[236:237], v188 offset:15872
	s_waitcnt lgkmcnt(10)
	v_mfma_f32_32x32x16_bf16 v[32:47], v[152:155], v[240:243], v[32:47]
	s_waitcnt lgkmcnt(8)
	v_mfma_f32_32x32x16_bf16 v[48:63], v[152:155], v[180:183], v[48:63]
	s_waitcnt lgkmcnt(6)
	v_mfma_f32_32x32x16_bf16 v[0:15], v[156:159], v[222:225], v[0:15]
	s_waitcnt lgkmcnt(4)
	v_mfma_f32_32x32x16_bf16 v[16:31], v[156:159], v[226:229], v[16:31]
	s_waitcnt lgkmcnt(2)
	v_mfma_f32_32x32x16_bf16 v[32:47], v[156:159], v[230:233], v[32:47]
	s_waitcnt lgkmcnt(0)
	v_mfma_f32_32x32x16_bf16 v[48:63], v[156:159], v[234:237], v[48:63]
	s_waitcnt vmcnt(0)
	s_setprio 0
	v_mov_b32_e32 v64, v197
	v_mov_b32_e32 v65, v197
	v_and_b32_e32 v80, 0x3fffffc0, v195
	s_mov_b32 s0, 0x10000
	v_permlane32_swap_b32_e32 v64, v65
	v_lshl_add_u32 v80, v80, 2, s0
	v_cmp_gt_u32_e32 vcc, 32, v179
	v_add_f32_e32 v64, v64, v65
	v_mov_b32_e32 v66, v191
	v_add_f32_e32 v64, 0xc2400000, v64
	s_nop 3
	s_and_saveexec_b64 s[0:1], vcc
	s_cbranch_execz .LBB0_439
	v_lshl_add_u32 v65, v66, 2, v80
	ds_write_b32 v65, v64
	s_branch .LBB0_439
